# fused LayerNorm epilogues: residual loads 12 in flight instead of one at a time; ln/shift/scale vectors read from an LDS copy so stores no longer gate each load
# speedup vs baseline: 1.1376x; 1.0284x over previous
.LBB0_180:
	s_lshl_b32 s4, s56, 8
	s_cmpk_lt_u32 s4, 0x4000
	s_cselect_b32 s0, s90, 0x3000
	s_cmp_gt_i32 s56, 31
	v_lshl_or_b32 v122, s42, 8, v126
	s_cselect_b32 s0, s0, 0
	v_or_b32_e32 v154, s62, v122
	s_lshl_b32 s10, s0, 2
	s_add_u32 s0, s52, s10
	v_ashrrev_i32_e32 v155, 31, v154
	s_addc_u32 s1, s53, 0
	v_lshlrev_b64 v[156:157], 2, v[154:155]
	v_lshl_add_u64 v[122:123], s[0:1], 0, v[156:157]
	s_add_i32 s0, s4, s13
	v_or_b32_e32 v158, s0, v162
	v_ashrrev_i32_e32 v159, 31, v158
	v_lshlrev_b64 v[160:161], 12, v[158:159]
	s_barrier
	global_load_dwordx4 v[150:153], v[122:123], off
	global_load_dwordx4 v[146:149], v[122:123], off offset:64
	global_load_dwordx4 v[142:145], v[122:123], off offset:512
	global_load_dwordx4 v[138:141], v[122:123], off offset:576
	v_lshl_add_u64 v[122:123], s[54:55], 0, v[160:161]
	v_lshl_add_u64 v[164:165], v[122:123], 0, v[156:157]
	s_mov_b32 s0, 0x3fb504f3
	s_mov_b64 s[6:7], 0x10000
	s_mov_b64 s[8:9], 0x50000
	v_and_b32_e32 v0, 63, v163
	s_mov_b64 s[14:15], 0x10000
	s_mov_b64 s[16:17], 0x50000
	v_lshl_add_u64 v[244:245], v[164:165], 0, 0
	global_load_dwordx4 v[174:177], v[244:245], off
	global_load_dwordx4 v[178:181], v[244:245], off offset:64
	global_load_dwordx4 v[192:195], v[244:245], off offset:512
	global_load_dwordx4 v[196:199], v[244:245], off offset:576
	v_lshl_add_u64 v[244:245], v[244:245], 0, s[6:7]
	global_load_dwordx4 v[200:203], v[244:245], off
	global_load_dwordx4 v[204:207], v[244:245], off offset:64
	global_load_dwordx4 v[224:227], v[244:245], off offset:512
	global_load_dwordx4 v[228:231], v[244:245], off offset:576
	v_lshl_add_u64 v[244:245], v[244:245], 0, s[6:7]
	global_load_dwordx4 v[232:235], v[244:245], off
	global_load_dwordx4 v[236:239], v[244:245], off offset:64
	global_load_dwordx4 v[240:243], v[244:245], off offset:512
	global_load_dwordx4 v[168:171], v[244:245], off offset:576
	s_waitcnt vmcnt(11)
	v_pk_mul_f32 v[124:125], v[176:177], s[0:1] op_sel_hi:[1,0]
	v_pk_mul_f32 v[122:123], v[174:175], s[0:1] op_sel_hi:[1,0]
	v_lshl_add_u64 v[244:245], v[244:245], 0, s[6:7]
	global_load_dwordx4 v[174:177], v[244:245], off
	v_pk_fma_f32 v[128:129], v[120:121], v[152:153], v[124:125]
	v_pk_fma_f32 v[126:127], v[118:119], v[150:151], v[122:123]
	s_waitcnt vmcnt(11)
	v_pk_mul_f32 v[120:121], v[180:181], s[0:1] op_sel_hi:[1,0]
	v_pk_mul_f32 v[118:119], v[178:179], s[0:1] op_sel_hi:[1,0]
	global_load_dwordx4 v[178:181], v[244:245], off offset:64
	v_pk_fma_f32 v[124:125], v[116:117], v[148:149], v[120:121]
	v_pk_fma_f32 v[122:123], v[114:115], v[146:147], v[118:119]
	s_waitcnt vmcnt(11)
	v_pk_mul_f32 v[116:117], v[194:195], s[0:1] op_sel_hi:[1,0]
	v_pk_mul_f32 v[114:115], v[192:193], s[0:1] op_sel_hi:[1,0]
	global_load_dwordx4 v[192:195], v[244:245], off offset:512
	v_pk_fma_f32 v[112:113], v[112:113], v[144:145], v[116:117]
	v_pk_fma_f32 v[110:111], v[110:111], v[142:143], v[114:115]
	v_lshl_add_u64 v[164:165], v[164:165], 0, s[6:7]
	s_waitcnt vmcnt(11)
	v_pk_mul_f32 v[116:117], v[198:199], s[0:1] op_sel_hi:[1,0]
	v_pk_mul_f32 v[114:115], v[196:197], s[0:1] op_sel_hi:[1,0]
	global_load_dwordx4 v[196:199], v[244:245], off offset:576
	v_pk_fma_f32 v[100:101], v[100:101], v[140:141], v[116:117]
	v_pk_fma_f32 v[98:99], v[98:99], v[138:139], v[114:115]
	s_nop 0
	s_waitcnt vmcnt(11)
	v_pk_mul_f32 v[116:117], v[202:203], s[0:1] op_sel_hi:[1,0]
	v_pk_mul_f32 v[114:115], v[200:201], s[0:1] op_sel_hi:[1,0]
	v_lshl_add_u64 v[244:245], v[244:245], 0, s[8:9]
	global_load_dwordx4 v[200:203], v[244:245], off
	v_pk_fma_f32 v[120:121], v[108:109], v[152:153], v[116:117]
	v_pk_fma_f32 v[118:119], v[106:107], v[150:151], v[114:115]
	s_waitcnt vmcnt(11)
	v_pk_mul_f32 v[108:109], v[206:207], s[0:1] op_sel_hi:[1,0]
	v_pk_mul_f32 v[106:107], v[204:205], s[0:1] op_sel_hi:[1,0]
	global_load_dwordx4 v[204:207], v[244:245], off offset:64
	v_pk_fma_f32 v[116:117], v[104:105], v[148:149], v[108:109]
	v_pk_fma_f32 v[114:115], v[102:103], v[146:147], v[106:107]
	s_waitcnt vmcnt(11)
	v_pk_mul_f32 v[104:105], v[226:227], s[0:1] op_sel_hi:[1,0]
	v_pk_mul_f32 v[102:103], v[224:225], s[0:1] op_sel_hi:[1,0]
	global_load_dwordx4 v[224:227], v[244:245], off offset:512
	v_pk_fma_f32 v[104:105], v[96:97], v[144:145], v[104:105]
	v_pk_fma_f32 v[102:103], v[94:95], v[142:143], v[102:103]
	v_lshl_add_u64 v[164:165], v[164:165], 0, s[6:7]
	s_waitcnt vmcnt(11)
	v_pk_mul_f32 v[96:97], v[230:231], s[0:1] op_sel_hi:[1,0]
	v_pk_mul_f32 v[94:95], v[228:229], s[0:1] op_sel_hi:[1,0]
	global_load_dwordx4 v[228:231], v[244:245], off offset:576
	v_pk_fma_f32 v[88:89], v[88:89], v[140:141], v[96:97]
	v_pk_fma_f32 v[86:87], v[86:87], v[138:139], v[94:95]
	s_nop 0
	s_waitcnt vmcnt(11)
	v_pk_mul_f32 v[96:97], v[234:235], s[0:1] op_sel_hi:[1,0]
	v_pk_mul_f32 v[94:95], v[232:233], s[0:1] op_sel_hi:[1,0]
	v_lshl_add_u64 v[244:245], v[244:245], 0, s[6:7]
	global_load_dwordx4 v[232:235], v[244:245], off
	v_pk_fma_f32 v[108:109], v[92:93], v[152:153], v[96:97]
	v_pk_fma_f32 v[106:107], v[90:91], v[150:151], v[94:95]
	s_waitcnt vmcnt(11)
	v_pk_mul_f32 v[92:93], v[238:239], s[0:1] op_sel_hi:[1,0]
	v_pk_mul_f32 v[90:91], v[236:237], s[0:1] op_sel_hi:[1,0]
	global_load_dwordx4 v[236:239], v[244:245], off offset:64
	v_pk_fma_f32 v[96:97], v[84:85], v[148:149], v[92:93]
	v_pk_fma_f32 v[94:95], v[82:83], v[146:147], v[90:91]
	s_waitcnt vmcnt(11)
	v_pk_mul_f32 v[84:85], v[242:243], s[0:1] op_sel_hi:[1,0]
	v_pk_mul_f32 v[82:83], v[240:241], s[0:1] op_sel_hi:[1,0]
	global_load_dwordx4 v[240:243], v[244:245], off offset:512
	v_pk_fma_f32 v[84:85], v[80:81], v[144:145], v[84:85]
	v_pk_fma_f32 v[82:83], v[78:79], v[142:143], v[82:83]
	v_lshl_add_u64 v[164:165], v[164:165], 0, s[6:7]
	s_waitcnt vmcnt(11)
	v_pk_mul_f32 v[80:81], v[170:171], s[0:1] op_sel_hi:[1,0]
	v_pk_mul_f32 v[78:79], v[168:169], s[0:1] op_sel_hi:[1,0]
	global_load_dwordx4 v[168:171], v[244:245], off offset:576
	v_pk_fma_f32 v[72:73], v[72:73], v[140:141], v[80:81]
	v_pk_fma_f32 v[70:71], v[70:71], v[138:139], v[78:79]
	s_nop 0
	s_waitcnt vmcnt(11)
	v_pk_mul_f32 v[80:81], v[176:177], s[0:1] op_sel_hi:[1,0]
	v_pk_mul_f32 v[78:79], v[174:175], s[0:1] op_sel_hi:[1,0]
	v_lshl_add_u64 v[244:245], v[244:245], 0, s[6:7]
	global_load_dwordx4 v[174:177], v[244:245], off
	v_pk_fma_f32 v[92:93], v[76:77], v[152:153], v[80:81]
	v_pk_fma_f32 v[90:91], v[74:75], v[150:151], v[78:79]
	s_waitcnt vmcnt(11)
	v_pk_mul_f32 v[76:77], v[180:181], s[0:1] op_sel_hi:[1,0]
	v_pk_mul_f32 v[74:75], v[178:179], s[0:1] op_sel_hi:[1,0]
	global_load_dwordx4 v[178:181], v[244:245], off offset:64
	v_pk_fma_f32 v[80:81], v[68:69], v[148:149], v[76:77]
	v_pk_fma_f32 v[78:79], v[66:67], v[146:147], v[74:75]
	s_waitcnt vmcnt(11)
	v_pk_mul_f32 v[68:69], v[194:195], s[0:1] op_sel_hi:[1,0]
	v_pk_mul_f32 v[66:67], v[192:193], s[0:1] op_sel_hi:[1,0]
	global_load_dwordx4 v[192:195], v[244:245], off offset:512
	v_pk_fma_f32 v[68:69], v[64:65], v[144:145], v[68:69]
	v_pk_fma_f32 v[66:67], v[62:63], v[142:143], v[66:67]
	v_lshl_add_u64 v[164:165], v[164:165], 0, s[8:9]
	s_waitcnt vmcnt(11)
	v_pk_mul_f32 v[64:65], v[198:199], s[0:1] op_sel_hi:[1,0]
	v_pk_mul_f32 v[62:63], v[196:197], s[0:1] op_sel_hi:[1,0]
	global_load_dwordx4 v[196:199], v[244:245], off offset:576
	v_pk_fma_f32 v[56:57], v[56:57], v[140:141], v[64:65]
	v_pk_fma_f32 v[54:55], v[54:55], v[138:139], v[62:63]
	s_nop 0
	s_waitcnt vmcnt(11)
	v_pk_mul_f32 v[64:65], v[202:203], s[0:1] op_sel_hi:[1,0]
	v_pk_mul_f32 v[62:63], v[200:201], s[0:1] op_sel_hi:[1,0]
	v_lshl_add_u64 v[244:245], v[244:245], 0, s[6:7]
	global_load_dwordx4 v[200:203], v[244:245], off
	v_pk_fma_f32 v[76:77], v[60:61], v[152:153], v[64:65]
	v_pk_fma_f32 v[74:75], v[58:59], v[150:151], v[62:63]
	s_waitcnt vmcnt(11)
	v_pk_mul_f32 v[60:61], v[206:207], s[0:1] op_sel_hi:[1,0]
	v_pk_mul_f32 v[58:59], v[204:205], s[0:1] op_sel_hi:[1,0]
	global_load_dwordx4 v[204:207], v[244:245], off offset:64
	v_pk_fma_f32 v[64:65], v[52:53], v[148:149], v[60:61]
	v_pk_fma_f32 v[62:63], v[50:51], v[146:147], v[58:59]
	s_waitcnt vmcnt(11)
	v_pk_mul_f32 v[52:53], v[226:227], s[0:1] op_sel_hi:[1,0]
	v_pk_mul_f32 v[50:51], v[224:225], s[0:1] op_sel_hi:[1,0]
	global_load_dwordx4 v[224:227], v[244:245], off offset:512
	v_pk_fma_f32 v[52:53], v[48:49], v[144:145], v[52:53]
	v_pk_fma_f32 v[50:51], v[46:47], v[142:143], v[50:51]
	v_lshl_add_u64 v[164:165], v[164:165], 0, s[6:7]
	s_waitcnt vmcnt(11)
	v_pk_mul_f32 v[48:49], v[230:231], s[0:1] op_sel_hi:[1,0]
	v_pk_mul_f32 v[46:47], v[228:229], s[0:1] op_sel_hi:[1,0]
	global_load_dwordx4 v[228:231], v[244:245], off offset:576
	v_pk_fma_f32 v[40:41], v[40:41], v[140:141], v[48:49]
	v_pk_fma_f32 v[38:39], v[38:39], v[138:139], v[46:47]
	s_nop 0
	s_waitcnt vmcnt(11)
	v_pk_mul_f32 v[48:49], v[234:235], s[0:1] op_sel_hi:[1,0]
	v_pk_mul_f32 v[46:47], v[232:233], s[0:1] op_sel_hi:[1,0]
	v_pk_fma_f32 v[60:61], v[44:45], v[152:153], v[48:49]
	v_pk_fma_f32 v[58:59], v[42:43], v[150:151], v[46:47]
	s_waitcnt vmcnt(10)
	v_pk_mul_f32 v[44:45], v[238:239], s[0:1] op_sel_hi:[1,0]
	v_pk_mul_f32 v[42:43], v[236:237], s[0:1] op_sel_hi:[1,0]
	v_pk_fma_f32 v[48:49], v[36:37], v[148:149], v[44:45]
	v_pk_fma_f32 v[46:47], v[34:35], v[146:147], v[42:43]
	s_waitcnt vmcnt(9)
	v_pk_mul_f32 v[36:37], v[242:243], s[0:1] op_sel_hi:[1,0]
	v_pk_mul_f32 v[34:35], v[240:241], s[0:1] op_sel_hi:[1,0]
	v_pk_fma_f32 v[36:37], v[32:33], v[144:145], v[36:37]
	v_pk_fma_f32 v[34:35], v[30:31], v[142:143], v[34:35]
	v_lshl_add_u64 v[164:165], v[164:165], 0, s[6:7]
	s_waitcnt vmcnt(8)
	v_pk_mul_f32 v[32:33], v[170:171], s[0:1] op_sel_hi:[1,0]
	v_pk_mul_f32 v[30:31], v[168:169], s[0:1] op_sel_hi:[1,0]
	v_pk_fma_f32 v[28:29], v[28:29], v[140:141], v[32:33]
	v_pk_fma_f32 v[26:27], v[26:27], v[138:139], v[30:31]
	s_nop 0
	s_waitcnt vmcnt(7)
	v_pk_mul_f32 v[32:33], v[176:177], s[0:1] op_sel_hi:[1,0]
	v_pk_mul_f32 v[30:31], v[174:175], s[0:1] op_sel_hi:[1,0]
	v_pk_fma_f32 v[44:45], v[24:25], v[152:153], v[32:33]
	v_pk_fma_f32 v[42:43], v[22:23], v[150:151], v[30:31]
	s_waitcnt vmcnt(6)
	v_pk_mul_f32 v[24:25], v[180:181], s[0:1] op_sel_hi:[1,0]
	v_pk_mul_f32 v[22:23], v[178:179], s[0:1] op_sel_hi:[1,0]
	v_pk_fma_f32 v[32:33], v[20:21], v[148:149], v[24:25]
	v_pk_fma_f32 v[30:31], v[18:19], v[146:147], v[22:23]
	s_waitcnt vmcnt(5)
	v_pk_mul_f32 v[20:21], v[194:195], s[0:1] op_sel_hi:[1,0]
	v_pk_mul_f32 v[18:19], v[192:193], s[0:1] op_sel_hi:[1,0]
	v_pk_fma_f32 v[24:25], v[16:17], v[144:145], v[20:21]
	v_pk_fma_f32 v[22:23], v[14:15], v[142:143], v[18:19]
	v_lshl_add_u64 v[164:165], v[164:165], 0, s[6:7]
	s_waitcnt vmcnt(4)
	v_pk_mul_f32 v[16:17], v[198:199], s[0:1] op_sel_hi:[1,0]
	v_pk_mul_f32 v[14:15], v[196:197], s[0:1] op_sel_hi:[1,0]
	v_pk_fma_f32 v[20:21], v[12:13], v[140:141], v[16:17]
	v_pk_fma_f32 v[18:19], v[10:11], v[138:139], v[14:15]
	s_nop 0
	s_waitcnt vmcnt(3)
	v_pk_mul_f32 v[12:13], v[202:203], s[0:1] op_sel_hi:[1,0]
	v_pk_mul_f32 v[10:11], v[200:201], s[0:1] op_sel_hi:[1,0]
	v_pk_fma_f32 v[16:17], v[136:137], v[152:153], v[12:13]
	v_pk_fma_f32 v[14:15], v[134:135], v[150:151], v[10:11]
	v_mov_b32_e32 v134, v126
	v_mov_b32_e32 v135, v129
	v_mov_b32_e32 v136, v122
	v_mov_b32_e32 v137, v125
	s_waitcnt vmcnt(2)
	v_pk_mul_f32 v[12:13], v[206:207], s[0:1] op_sel_hi:[1,0]
	v_pk_mul_f32 v[10:11], v[204:205], s[0:1] op_sel_hi:[1,0]
	v_pk_fma_f32 v[12:13], v[132:133], v[148:149], v[12:13]
	v_pk_fma_f32 v[10:11], v[130:131], v[146:147], v[10:11]
	s_waitcnt vmcnt(1)
	v_pk_mul_f32 v[132:133], v[226:227], s[0:1] op_sel_hi:[1,0]
	v_pk_mul_f32 v[130:131], v[224:225], s[0:1] op_sel_hi:[1,0]
	v_pk_fma_f32 v[8:9], v[8:9], v[144:145], v[132:133]
	v_pk_fma_f32 v[6:7], v[6:7], v[142:143], v[130:131]
	s_waitcnt vmcnt(0)
	v_pk_mul_f32 v[132:133], v[230:231], s[0:1] op_sel_hi:[1,0]
	v_pk_mul_f32 v[130:131], v[228:229], s[0:1] op_sel_hi:[1,0]
	v_pk_fma_f32 v[4:5], v[4:5], v[140:141], v[132:133]
	v_pk_fma_f32 v[2:3], v[2:3], v[138:139], v[130:131]
	v_lshl_add_u64 v[130:131], v[164:165], 0, s[8:9]
	v_xor_b32_e32 v132, 32, v214
	v_and_b32_e32 v131, 64, v214
	v_xor_b32_e32 v130, 16, v214
	v_add_u32_e32 v131, 64, v131
	v_cmp_lt_i32_e32 vcc, v130, v131
	v_mov_b32_e32 v133, v128
	v_add_f32_e32 v139, v112, v113
	v_cndmask_b32_e32 v130, v214, v130, vcc
	v_cmp_lt_i32_e32 vcc, v132, v131
	v_mov_b32_e32 v138, v99
	v_lshlrev_b32_e32 v130, 2, v130
	v_cndmask_b32_e32 v131, v214, v132, vcc
	v_mov_b32_e32 v132, v127
	v_pk_add_f32 v[132:133], v[132:133], v[134:135]
	v_mov_b32_e32 v134, v123
	v_mov_b32_e32 v135, v124
	v_pk_add_f32 v[134:135], v[134:135], v[136:137]
	v_add_f32_e32 v132, v132, v133
	v_pk_add_f32 v[134:135], v[134:135], v[134:135] op_sel_hi:[0,1]
	v_add_f32_e32 v133, 0, v132
	v_add_f32_e32 v137, v110, v111
	v_mov_b32_e32 v136, v98
	v_mov_b32_e32 v134, v100
	v_mov_b32_e32 v132, v101
	v_pk_add_f32 v[136:137], v[136:137], v[138:139]
	v_pk_add_f32 v[132:133], v[134:135], v[132:133]
	v_lshlrev_b32_e32 v131, 2, v131
	v_pk_add_f32 v[132:133], v[136:137], v[132:133]
	s_lshl_b32 s0, s38, 3
	v_add_f32_e32 v132, v132, v133
	ds_bpermute_b32 v133, v130, v132
	v_cmp_gt_u32_e32 vcc, 16, v0
	s_add_i32 s5, s0, 0
	s_waitcnt lgkmcnt(0)
	v_add_f32_e32 v132, v132, v133
	ds_bpermute_b32 v133, v131, v132
	s_waitcnt lgkmcnt(0)
	v_add_f32_e32 v132, v132, v133
	v_fmamk_f32 v134, v132, 0xbc800000, v129
	v_fmamk_f32 v136, v132, 0xbc800000, v127
	v_fmamk_f32 v133, v132, 0xbc800000, v128
	v_fmamk_f32 v135, v132, 0xbc800000, v126
	v_mul_f32_e32 v136, v136, v136
	v_mul_f32_e32 v134, v134, v134
	v_fmac_f32_e32 v136, v135, v135
	v_fmac_f32_e32 v134, v133, v133
	v_fmamk_f32 v135, v132, 0xbc800000, v125
	v_fmamk_f32 v137, v132, 0xbc800000, v123
	v_add_f32_e32 v133, v136, v134
	v_fmamk_f32 v134, v132, 0xbc800000, v124
	v_fmamk_f32 v136, v132, 0xbc800000, v122
	v_mul_f32_e32 v137, v137, v137
	v_mul_f32_e32 v135, v135, v135
	v_fmac_f32_e32 v137, v136, v136
	v_fmac_f32_e32 v135, v134, v134
	v_add_f32_e32 v134, v137, v135
	v_fmamk_f32 v135, v132, 0xbc800000, v113
	v_fmamk_f32 v137, v132, 0xbc800000, v111
	v_add_f32_e32 v133, v133, v134
	v_fmamk_f32 v134, v132, 0xbc800000, v112
	v_fmamk_f32 v136, v132, 0xbc800000, v110
	v_mul_f32_e32 v137, v137, v137
	v_mul_f32_e32 v135, v135, v135
	v_fmac_f32_e32 v137, v136, v136
	v_fmac_f32_e32 v135, v134, v134
	v_add_f32_e32 v134, v137, v135
	v_fmamk_f32 v135, v132, 0xbc800000, v101
	v_fmamk_f32 v137, v132, 0xbc800000, v99
	v_add_f32_e32 v133, v134, v133
	v_fmamk_f32 v134, v132, 0xbc800000, v100
	v_fmamk_f32 v136, v132, 0xbc800000, v98
	v_mul_f32_e32 v137, v137, v137
	v_mul_f32_e32 v135, v135, v135
	v_fmac_f32_e32 v137, v136, v136
	v_fmac_f32_e32 v135, v134, v134
	v_add_f32_e32 v134, v137, v135
	v_add_f32_e32 v133, v134, v133
	ds_bpermute_b32 v134, v130, v133
	s_waitcnt lgkmcnt(0)
	v_add_f32_e32 v133, v133, v134
	ds_bpermute_b32 v134, v131, v133
	s_and_saveexec_b64 s[0:1], vcc
	s_mov_b32 s72, 0xa000
	v_readlane_b32 s18, v253, 49
	s_cbranch_execz .LBB0_182
	s_lshl_b32 s6, s33, 11
	s_add_i32 s6, s5, s6
	v_mul_f32_e32 v132, 0x3c800000, v132
	v_lshl_add_u32 v135, v162, 5, s6
	s_waitcnt lgkmcnt(0)
	v_add_f32_e32 v133, v133, v134
	ds_write_b64 v135, v[132:133]

.LBB0_220:
	s_or_b64 exec, exec, s[0:1]
	v_readfirstlane_b32 vcc_lo, v191
	s_nop 3
	s_lshr_b32 vcc_lo, vcc_lo, 6
	s_cmp_gt_u32 vcc_lo, 3
	s_cbranch_scc1 .Lfln_fill_done_a
	s_add_u32 s0, s46, s10
	s_addc_u32 s1, s47, 0
	s_cmp_eq_u32 vcc_lo, 3
	s_cselect_b32 vcc_hi, 0x1000, 0
	s_add_u32 s0, s0, vcc_hi
	s_addc_u32 s1, s1, 0
	s_cmp_eq_u32 vcc_lo, 0
	s_cselect_b32 s0, s48, s0
	s_cselect_b32 s1, s49, s1
	s_cmp_eq_u32 vcc_lo, 1
	s_cselect_b32 s0, s50, s0
	s_cselect_b32 s1, s51, s1
	s_cmp_lt_u32 vcc_lo, 2
	s_cbranch_scc1 .Lfln_fill_go_a
	s_cmp_eq_u64 s[46:47], 0
	s_cbranch_scc1 .Lfln_fill_done_a
.Lfln_fill_go_a:
	v_and_b32_e32 v172, 0xfffffc00, v156
	v_lshl_add_u32 v172, v214, 4, v172
	global_load_dwordx4 v[168:171], v172, s[0:1]
	s_lshl_b32 vcc_hi, vcc_lo, 10
	v_lshlrev_b32_e32 v173, 4, v214
	v_add_u32_e32 v173, vcc_hi, v173
	s_waitcnt vmcnt(0)
	ds_write_b128 v173, v[168:171] offset:16384
.Lfln_fill_done_a:
	v_and_b32_e32 v166, 0x3ff, v156
	s_waitcnt lgkmcnt(0)
	s_barrier
	v_lshl_add_u64 v[132:133], s[48:49], 0, v[156:157]
	v_lshl_add_u64 v[134:135], s[50:51], 0, v[156:157]
	ds_read_b128 v[146:149], v166 offset:16384
	ds_read_b128 v[150:153], v166 offset:17408
	v_readlane_b32 s4, v254, 8
	v_readlane_b32 s5, v254, 9
	v_lshlrev_b64 v[136:137], 11, v[158:159]
	s_add_u32 s0, s46, s10
	v_lshl_add_u64 v[130:131], s[4:5], 0, v[160:161]
	v_readlane_b32 s4, v254, 12
	v_readlane_b32 s5, v254, 13
	v_lshl_add_u64 v[138:139], v[130:131], 0, v[156:157]
	s_addc_u32 s1, s47, 0
	v_lshl_add_u64 v[130:131], s[4:5], 0, v[136:137]
	s_lshl_b32 s4, s13, 3
	v_lshl_add_u64 v[140:141], v[154:155], 1, v[130:131]
	v_lshl_add_u64 v[130:131], s[0:1], 0, v[156:157]
	s_add_i32 s0, s4, 0
	v_lshl_add_u32 v0, v162, 3, s0
	ds_read_b64 v[142:143], v0 offset:8192
	s_cmp_lg_u64 s[46:47], 0
	s_mov_b64 s[0:1], 0x1000
	s_waitcnt lgkmcnt(0)
	v_cmp_eq_u32_e64 s[40:41], 0, v144
	v_lshl_add_u64 v[136:137], v[130:131], 0, s[0:1]
	s_waitcnt lgkmcnt(0)
	v_sub_f32_e32 v129, v129, v142
	v_sub_f32_e32 v128, v128, v142
	v_sub_f32_e32 v127, v127, v142
	v_sub_f32_e32 v126, v126, v142
	v_pk_mul_f32 v[126:127], v[142:143], v[126:127] op_sel:[1,0]
	v_pk_mul_f32 v[128:129], v[142:143], v[128:129] op_sel:[1,0]
	s_cselect_b64 s[0:1], -1, 0
	s_cmp_eq_u64 s[46:47], 0
	v_readlane_b32 s6, v254, 10
	v_readlane_b32 s7, v254, 11
	s_waitcnt lgkmcnt(0)
	v_pk_fma_f32 v[128:129], v[148:149], v[128:129], v[152:153]
	v_pk_fma_f32 v[126:127], v[146:147], v[126:127], v[150:151]
	v_cndmask_b32_e64 v129, v215, v129, s[40:41]
	v_cndmask_b32_e64 v128, v215, v128, s[40:41]
	v_cndmask_b32_e64 v127, v215, v127, s[40:41]
	v_cndmask_b32_e64 v126, v215, v126, s[40:41]
	global_store_dwordx4 v[138:139], v[126:129], off
	s_cbranch_scc1 .LBB0_222
	ds_read_b128 v[144:147], v166 offset:19456
	ds_read_b128 v[148:151], v166 offset:18432
	s_waitcnt lgkmcnt(0)
	v_pk_add_f32 v[146:147], v[146:147], 1.0 op_sel_hi:[1,0]
	v_pk_add_f32 v[144:145], v[144:145], 1.0 op_sel_hi:[1,0]
	s_waitcnt lgkmcnt(0)
	v_pk_fma_f32 v[128:129], v[128:129], v[146:147], v[150:151]
	v_pk_fma_f32 v[126:127], v[126:127], v[144:145], v[148:149]
	s_nop 0
	v_cvt_pk_bf16_f32 v126, v126, v127
	v_cvt_pk_bf16_f32 v127, v128, v129
	global_store_dwordx2 v[140:141], v[126:127], off
.LBB0_222:
	ds_read_b128 v[144:147], v166 offset:16448
	ds_read_b128 v[148:151], v166 offset:17472
	v_mov_b32_e32 v126, v143
	v_mov_b32_e32 v127, v143
	v_sub_f32_e32 v123, v123, v142
	v_sub_f32_e32 v122, v122, v142
	v_sub_f32_e32 v125, v125, v142
	v_sub_f32_e32 v124, v124, v142
	v_mov_b32_e32 v128, v143
	v_mov_b32_e32 v129, v143
	v_pk_mul_f32 v[124:125], v[128:129], v[124:125]
	v_pk_mul_f32 v[122:123], v[126:127], v[122:123]
	s_andn2_b64 vcc, exec, s[0:1]
	s_waitcnt lgkmcnt(0)
	v_pk_fma_f32 v[122:123], v[122:123], v[144:145], v[148:149]
	v_pk_fma_f32 v[124:125], v[124:125], v[146:147], v[150:151]
	v_cndmask_b32_e64 v144, 0, 1, s[0:1]
	v_cndmask_b32_e64 v125, v215, v125, s[40:41]
	v_cndmask_b32_e64 v124, v215, v124, s[40:41]
	v_cndmask_b32_e64 v123, v215, v123, s[40:41]
	v_cndmask_b32_e64 v122, v215, v122, s[40:41]
	v_cmp_ne_u32_e64 s[42:43], 1, v144
	global_store_dwordx4 v[138:139], v[122:125], off offset:64
	s_cbranch_vccnz .LBB0_224
	v_add_co_u32_e32 v144, vcc, 0x1000, v130
	s_nop 1
	v_addc_co_u32_e32 v145, vcc, 0, v131, vcc
	ds_read_b128 v[144:147], v166 offset:19520
	s_nop 0
	ds_read_b128 v[148:151], v166 offset:18496
	s_waitcnt lgkmcnt(0)
	v_pk_add_f32 v[146:147], v[146:147], 1.0 op_sel_hi:[1,0]
	v_pk_add_f32 v[144:145], v[144:145], 1.0 op_sel_hi:[1,0]
	s_waitcnt lgkmcnt(0)
	v_pk_fma_f32 v[124:125], v[124:125], v[146:147], v[150:151]
	v_pk_fma_f32 v[122:123], v[122:123], v[144:145], v[148:149]
	s_nop 0
	v_cvt_pk_bf16_f32 v122, v122, v123
	v_cvt_pk_bf16_f32 v123, v124, v125
	global_store_dwordx2 v[140:141], v[122:123], off offset:32
.LBB0_224:
	ds_read_b128 v[122:125], v166 offset:16896
	ds_read_b128 v[144:147], v166 offset:17920
	v_sub_f32_e32 v111, v111, v142
	v_sub_f32_e32 v110, v110, v142
	v_sub_f32_e32 v113, v113, v142
	v_sub_f32_e32 v112, v112, v142
	v_pk_mul_f32 v[112:113], v[128:129], v[112:113]
	v_pk_mul_f32 v[110:111], v[126:127], v[110:111]
	s_and_b64 vcc, exec, s[42:43]
	s_waitcnt lgkmcnt(0)
	v_pk_fma_f32 v[110:111], v[110:111], v[122:123], v[144:145]
	v_pk_fma_f32 v[112:113], v[112:113], v[124:125], v[146:147]
	v_cndmask_b32_e64 v111, v215, v111, s[40:41]
	v_cndmask_b32_e64 v113, v215, v113, s[40:41]
	v_cndmask_b32_e64 v112, v215, v112, s[40:41]
	v_cndmask_b32_e64 v110, v215, v110, s[40:41]
	global_store_dwordx4 v[138:139], v[110:113], off offset:512
	s_cbranch_vccnz .LBB0_226
	v_add_co_u32_e32 v122, vcc, 0x1000, v130
	s_nop 1
	v_addc_co_u32_e32 v123, vcc, 0, v131, vcc
	ds_read_b128 v[122:125], v166 offset:19968
	s_nop 0
	ds_read_b128 v[144:147], v166 offset:18944
	s_waitcnt lgkmcnt(0)
	v_pk_add_f32 v[124:125], v[124:125], 1.0 op_sel_hi:[1,0]
	v_pk_add_f32 v[122:123], v[122:123], 1.0 op_sel_hi:[1,0]
	s_waitcnt lgkmcnt(0)
	v_pk_fma_f32 v[112:113], v[112:113], v[124:125], v[146:147]
	v_pk_fma_f32 v[110:111], v[110:111], v[122:123], v[144:145]
	s_nop 0
	v_cvt_pk_bf16_f32 v110, v110, v111
	v_cvt_pk_bf16_f32 v111, v112, v113
	global_store_dwordx2 v[140:141], v[110:111], off offset:256
.LBB0_226:
	ds_read_b128 v[110:113], v166 offset:16960
	ds_read_b128 v[122:125], v166 offset:17984
	v_sub_f32_e32 v99, v99, v142
	v_sub_f32_e32 v98, v98, v142
	v_sub_f32_e32 v101, v101, v142
	v_sub_f32_e32 v100, v100, v142
	v_mov_b32_e32 v142, v143
	v_pk_mul_f32 v[100:101], v[142:143], v[100:101]
	v_pk_mul_f32 v[98:99], v[126:127], v[98:99]
	s_and_b64 vcc, exec, s[42:43]
	s_waitcnt lgkmcnt(0)
	v_pk_fma_f32 v[98:99], v[98:99], v[110:111], v[122:123]
	v_pk_fma_f32 v[100:101], v[100:101], v[112:113], v[124:125]
	v_cndmask_b32_e64 v99, v215, v99, s[40:41]
	v_cndmask_b32_e64 v101, v215, v101, s[40:41]
	v_cndmask_b32_e64 v100, v215, v100, s[40:41]
	v_cndmask_b32_e64 v98, v215, v98, s[40:41]
	global_store_dwordx4 v[138:139], v[98:101], off offset:576
	s_cbranch_vccnz .LBB0_228
	v_add_co_u32_e32 v110, vcc, 0x1000, v130
	s_nop 1
	v_addc_co_u32_e32 v111, vcc, 0, v131, vcc
	ds_read_b128 v[110:113], v166 offset:20032
	s_nop 0
	ds_read_b128 v[122:125], v166 offset:19008
	s_waitcnt lgkmcnt(0)
	v_pk_add_f32 v[112:113], v[112:113], 1.0 op_sel_hi:[1,0]
	v_pk_add_f32 v[110:111], v[110:111], 1.0 op_sel_hi:[1,0]
	s_waitcnt lgkmcnt(0)
	v_pk_fma_f32 v[100:101], v[100:101], v[112:113], v[124:125]
	v_pk_fma_f32 v[98:99], v[98:99], v[110:111], v[122:123]
	s_nop 0
	v_cvt_pk_bf16_f32 v98, v98, v99
	v_cvt_pk_bf16_f32 v99, v100, v101
	global_store_dwordx2 v[140:141], v[98:99], off offset:288
.LBB0_228:
	s_mov_b64 s[0:1], 0x8000
	v_lshl_add_u64 v[110:111], v[138:139], 0, s[14:15]
	v_lshl_add_u64 v[112:113], v[140:141], 0, s[0:1]
	ds_read_b128 v[98:101], v166 offset:16384
	ds_read_b128 v[124:127], v166 offset:17408
	ds_read_b64 v[122:123], v0 offset:8320
	s_and_b64 vcc, exec, s[42:43]
	s_waitcnt lgkmcnt(0)
	v_sub_f32_e32 v119, v119, v122
	v_sub_f32_e32 v118, v118, v122
	v_sub_f32_e32 v121, v121, v122
	v_sub_f32_e32 v120, v120, v122
	v_pk_mul_f32 v[120:121], v[122:123], v[120:121] op_sel:[1,0]
	v_pk_mul_f32 v[118:119], v[122:123], v[118:119] op_sel:[1,0]
	s_waitcnt lgkmcnt(0)
	v_pk_fma_f32 v[100:101], v[100:101], v[120:121], v[126:127]
	v_pk_fma_f32 v[98:99], v[98:99], v[118:119], v[124:125]
	v_cndmask_b32_e64 v101, v215, v101, s[40:41]
	v_cndmask_b32_e64 v100, v215, v100, s[40:41]
	v_cndmask_b32_e64 v99, v215, v99, s[40:41]
	v_cndmask_b32_e64 v98, v215, v98, s[40:41]
	global_store_dwordx4 v[110:111], v[98:101], off
	s_cbranch_vccnz .LBB0_230
	ds_read_b128 v[118:121], v166 offset:19456
	ds_read_b128 v[124:127], v166 offset:18432
	s_waitcnt lgkmcnt(0)
	v_pk_add_f32 v[120:121], v[120:121], 1.0 op_sel_hi:[1,0]
	v_pk_add_f32 v[118:119], v[118:119], 1.0 op_sel_hi:[1,0]
	s_waitcnt lgkmcnt(0)
	v_pk_fma_f32 v[100:101], v[100:101], v[120:121], v[126:127]
	v_pk_fma_f32 v[98:99], v[98:99], v[118:119], v[124:125]
	s_nop 0
	v_cvt_pk_bf16_f32 v98, v98, v99
	v_cvt_pk_bf16_f32 v99, v100, v101
	global_store_dwordx2 v[112:113], v[98:99], off
.LBB0_230:
	ds_read_b128 v[98:101], v166 offset:16448
	ds_read_b128 v[124:127], v166 offset:17472
	v_mov_b32_e32 v118, v123
	v_mov_b32_e32 v119, v123
	v_sub_f32_e32 v121, v115, v122
	v_sub_f32_e32 v120, v114, v122
	v_sub_f32_e32 v117, v117, v122
	v_sub_f32_e32 v116, v116, v122
	v_mov_b32_e32 v114, v123
	v_mov_b32_e32 v115, v123
	v_pk_mul_f32 v[116:117], v[114:115], v[116:117]
	v_pk_mul_f32 v[120:121], v[118:119], v[120:121]
	s_and_b64 vcc, exec, s[42:43]
	s_waitcnt lgkmcnt(0)
	v_pk_fma_f32 v[98:99], v[120:121], v[98:99], v[124:125]
	v_pk_fma_f32 v[100:101], v[116:117], v[100:101], v[126:127]
	v_cndmask_b32_e64 v99, v215, v99, s[40:41]
	v_cndmask_b32_e64 v101, v215, v101, s[40:41]
	v_cndmask_b32_e64 v100, v215, v100, s[40:41]
	v_cndmask_b32_e64 v98, v215, v98, s[40:41]
	global_store_dwordx4 v[110:111], v[98:101], off offset:64
	s_cbranch_vccnz .LBB0_232
	v_add_co_u32_e32 v116, vcc, 0x1000, v130
	s_nop 1
	v_addc_co_u32_e32 v117, vcc, 0, v131, vcc
	ds_read_b128 v[124:127], v166 offset:19520
	ds_read_b128 v[138:141], v166 offset:18496
	s_waitcnt lgkmcnt(0)
	v_pk_add_f32 v[116:117], v[126:127], 1.0 op_sel_hi:[1,0]
	v_pk_add_f32 v[120:121], v[124:125], 1.0 op_sel_hi:[1,0]
	s_waitcnt lgkmcnt(0)
	v_pk_fma_f32 v[100:101], v[100:101], v[116:117], v[140:141]
	v_pk_fma_f32 v[98:99], v[98:99], v[120:121], v[138:139]
	s_nop 0
	v_cvt_pk_bf16_f32 v98, v98, v99
	v_cvt_pk_bf16_f32 v99, v100, v101
	global_store_dwordx2 v[112:113], v[98:99], off offset:32
.LBB0_232:
	ds_read_b128 v[98:101], v166 offset:16896
	ds_read_b128 v[124:127], v166 offset:17920
	v_sub_f32_e32 v103, v103, v122
	v_sub_f32_e32 v102, v102, v122
	v_sub_f32_e32 v105, v105, v122
	v_sub_f32_e32 v104, v104, v122
	v_pk_mul_f32 v[104:105], v[114:115], v[104:105]
	v_pk_mul_f32 v[102:103], v[118:119], v[102:103]
	s_and_b64 vcc, exec, s[42:43]
	s_waitcnt lgkmcnt(0)
	v_pk_fma_f32 v[98:99], v[102:103], v[98:99], v[124:125]
	v_pk_fma_f32 v[100:101], v[104:105], v[100:101], v[126:127]
	v_cndmask_b32_e64 v99, v215, v99, s[40:41]
	v_cndmask_b32_e64 v101, v215, v101, s[40:41]
	v_cndmask_b32_e64 v100, v215, v100, s[40:41]
	v_cndmask_b32_e64 v98, v215, v98, s[40:41]
	global_store_dwordx4 v[110:111], v[98:101], off offset:512
	s_cbranch_vccnz .LBB0_234
	v_add_co_u32_e32 v102, vcc, 0x1000, v130
	s_nop 1
	v_addc_co_u32_e32 v103, vcc, 0, v131, vcc
	ds_read_b128 v[102:105], v166 offset:19968
	s_nop 0
	ds_read_b128 v[114:117], v166 offset:18944
	s_waitcnt lgkmcnt(0)
	v_pk_add_f32 v[104:105], v[104:105], 1.0 op_sel_hi:[1,0]
	v_pk_add_f32 v[102:103], v[102:103], 1.0 op_sel_hi:[1,0]
	s_waitcnt lgkmcnt(0)
	v_pk_fma_f32 v[100:101], v[100:101], v[104:105], v[116:117]
	v_pk_fma_f32 v[98:99], v[98:99], v[102:103], v[114:115]
	s_nop 0
	v_cvt_pk_bf16_f32 v98, v98, v99
	v_cvt_pk_bf16_f32 v99, v100, v101
	global_store_dwordx2 v[112:113], v[98:99], off offset:256
.LBB0_234:
	ds_read_b128 v[98:101], v166 offset:16960
	ds_read_b128 v[102:105], v166 offset:17984
	v_sub_f32_e32 v87, v87, v122
	v_sub_f32_e32 v86, v86, v122
	v_sub_f32_e32 v89, v89, v122
	v_sub_f32_e32 v88, v88, v122
	v_mov_b32_e32 v122, v123
	v_pk_mul_f32 v[88:89], v[122:123], v[88:89]
	v_pk_mul_f32 v[86:87], v[118:119], v[86:87]
	s_and_b64 vcc, exec, s[42:43]
	s_waitcnt lgkmcnt(0)
	v_pk_fma_f32 v[86:87], v[86:87], v[98:99], v[102:103]
	v_pk_fma_f32 v[88:89], v[88:89], v[100:101], v[104:105]
	v_cndmask_b32_e64 v87, v215, v87, s[40:41]
	v_cndmask_b32_e64 v89, v215, v89, s[40:41]
	v_cndmask_b32_e64 v88, v215, v88, s[40:41]
	v_cndmask_b32_e64 v86, v215, v86, s[40:41]
	global_store_dwordx4 v[110:111], v[86:89], off offset:576
	s_cbranch_vccnz .LBB0_236
	v_add_co_u32_e32 v98, vcc, 0x1000, v130
	s_nop 1
	v_addc_co_u32_e32 v99, vcc, 0, v131, vcc
	ds_read_b128 v[98:101], v166 offset:20032
	s_nop 0
	ds_read_b128 v[102:105], v166 offset:19008
	s_waitcnt lgkmcnt(0)
	v_pk_add_f32 v[100:101], v[100:101], 1.0 op_sel_hi:[1,0]
	v_pk_add_f32 v[98:99], v[98:99], 1.0 op_sel_hi:[1,0]
	s_waitcnt lgkmcnt(0)
	v_pk_fma_f32 v[88:89], v[88:89], v[100:101], v[104:105]
	v_pk_fma_f32 v[86:87], v[86:87], v[98:99], v[102:103]
	s_nop 0
	v_cvt_pk_bf16_f32 v86, v86, v87
	v_cvt_pk_bf16_f32 v87, v88, v89
	global_store_dwordx2 v[112:113], v[86:87], off offset:288
.LBB0_236:
	v_lshl_add_u64 v[98:99], v[110:111], 0, s[14:15]
	v_lshl_add_u64 v[100:101], v[112:113], 0, s[0:1]
	ds_read_b128 v[86:89], v166 offset:16384
	ds_read_b128 v[110:113], v166 offset:17408
	ds_read_b64 v[102:103], v0 offset:8448
	s_and_b64 vcc, exec, s[42:43]
	s_waitcnt lgkmcnt(0)
	v_sub_f32_e32 v105, v107, v102
	v_sub_f32_e32 v104, v106, v102
	v_sub_f32_e32 v107, v109, v102
	v_sub_f32_e32 v106, v108, v102
	v_pk_mul_f32 v[106:107], v[102:103], v[106:107] op_sel:[1,0]
	v_pk_mul_f32 v[104:105], v[102:103], v[104:105] op_sel:[1,0]
	s_waitcnt lgkmcnt(0)
	v_pk_fma_f32 v[88:89], v[88:89], v[106:107], v[112:113]
	v_pk_fma_f32 v[86:87], v[86:87], v[104:105], v[110:111]
	v_cndmask_b32_e64 v89, v215, v89, s[40:41]
	v_cndmask_b32_e64 v88, v215, v88, s[40:41]
	v_cndmask_b32_e64 v87, v215, v87, s[40:41]
	v_cndmask_b32_e64 v86, v215, v86, s[40:41]
	global_store_dwordx4 v[98:99], v[86:89], off
	s_cbranch_vccnz .LBB0_238
	ds_read_b128 v[104:107], v166 offset:19456
	ds_read_b128 v[108:111], v166 offset:18432
	s_waitcnt lgkmcnt(0)
	v_pk_add_f32 v[106:107], v[106:107], 1.0 op_sel_hi:[1,0]
	v_pk_add_f32 v[104:105], v[104:105], 1.0 op_sel_hi:[1,0]
	s_waitcnt lgkmcnt(0)
	v_pk_fma_f32 v[88:89], v[88:89], v[106:107], v[110:111]
	v_pk_fma_f32 v[86:87], v[86:87], v[104:105], v[108:109]
	s_nop 0
	v_cvt_pk_bf16_f32 v86, v86, v87
	v_cvt_pk_bf16_f32 v87, v88, v89
	global_store_dwordx2 v[100:101], v[86:87], off
.LBB0_238:
	ds_read_b128 v[86:89], v166 offset:16448
	ds_read_b128 v[106:109], v166 offset:17472
	v_mov_b32_e32 v104, v103
	v_mov_b32_e32 v105, v103
	v_sub_f32_e32 v111, v95, v102
	v_sub_f32_e32 v110, v94, v102
	v_sub_f32_e32 v97, v97, v102
	v_sub_f32_e32 v96, v96, v102
	v_mov_b32_e32 v94, v103
	v_mov_b32_e32 v95, v103
	v_pk_mul_f32 v[96:97], v[94:95], v[96:97]
	v_pk_mul_f32 v[110:111], v[104:105], v[110:111]
	s_and_b64 vcc, exec, s[42:43]
	s_waitcnt lgkmcnt(0)
	v_pk_fma_f32 v[86:87], v[110:111], v[86:87], v[106:107]
	v_pk_fma_f32 v[88:89], v[96:97], v[88:89], v[108:109]
	v_cndmask_b32_e64 v87, v215, v87, s[40:41]
	v_cndmask_b32_e64 v89, v215, v89, s[40:41]
	v_cndmask_b32_e64 v88, v215, v88, s[40:41]
	v_cndmask_b32_e64 v86, v215, v86, s[40:41]
	global_store_dwordx4 v[98:99], v[86:89], off offset:64
	s_cbranch_vccnz .LBB0_240
	v_add_co_u32_e32 v96, vcc, 0x1000, v130
	s_nop 1
	v_addc_co_u32_e32 v97, vcc, 0, v131, vcc
	ds_read_b128 v[106:109], v166 offset:19520
	ds_read_b128 v[110:113], v166 offset:18496
	s_waitcnt lgkmcnt(0)
	v_pk_add_f32 v[96:97], v[108:109], 1.0 op_sel_hi:[1,0]
	v_pk_add_f32 v[106:107], v[106:107], 1.0 op_sel_hi:[1,0]
	s_waitcnt lgkmcnt(0)
	v_pk_fma_f32 v[88:89], v[88:89], v[96:97], v[112:113]
	v_pk_fma_f32 v[86:87], v[86:87], v[106:107], v[110:111]
	s_nop 0
	v_cvt_pk_bf16_f32 v86, v86, v87
	v_cvt_pk_bf16_f32 v87, v88, v89
	global_store_dwordx2 v[100:101], v[86:87], off offset:32
.LBB0_240:
	ds_read_b128 v[86:89], v166 offset:16896
	ds_read_b128 v[106:109], v166 offset:17920
	v_sub_f32_e32 v83, v83, v102
	v_sub_f32_e32 v82, v82, v102
	v_sub_f32_e32 v85, v85, v102
	v_sub_f32_e32 v84, v84, v102
	v_pk_mul_f32 v[84:85], v[94:95], v[84:85]
	v_pk_mul_f32 v[82:83], v[104:105], v[82:83]
	s_and_b64 vcc, exec, s[42:43]
	s_waitcnt lgkmcnt(0)
	v_pk_fma_f32 v[82:83], v[82:83], v[86:87], v[106:107]
	v_pk_fma_f32 v[84:85], v[84:85], v[88:89], v[108:109]
	v_cndmask_b32_e64 v83, v215, v83, s[40:41]
	v_cndmask_b32_e64 v85, v215, v85, s[40:41]
	v_cndmask_b32_e64 v84, v215, v84, s[40:41]
	v_cndmask_b32_e64 v82, v215, v82, s[40:41]
	global_store_dwordx4 v[98:99], v[82:85], off offset:512
	s_cbranch_vccnz .LBB0_242
	v_add_co_u32_e32 v86, vcc, 0x1000, v130
	s_nop 1
	v_addc_co_u32_e32 v87, vcc, 0, v131, vcc
	ds_read_b128 v[86:89], v166 offset:19968
	s_nop 0
	ds_read_b128 v[94:97], v166 offset:18944
	s_waitcnt lgkmcnt(0)
	v_pk_add_f32 v[88:89], v[88:89], 1.0 op_sel_hi:[1,0]
	v_pk_add_f32 v[86:87], v[86:87], 1.0 op_sel_hi:[1,0]
	s_waitcnt lgkmcnt(0)
	v_pk_fma_f32 v[84:85], v[84:85], v[88:89], v[96:97]
	v_pk_fma_f32 v[82:83], v[82:83], v[86:87], v[94:95]
	s_nop 0
	v_cvt_pk_bf16_f32 v82, v82, v83
	v_cvt_pk_bf16_f32 v83, v84, v85
	global_store_dwordx2 v[100:101], v[82:83], off offset:256
.LBB0_242:
	ds_read_b128 v[82:85], v166 offset:16960
	ds_read_b128 v[86:89], v166 offset:17984
	v_sub_f32_e32 v71, v71, v102
	v_sub_f32_e32 v70, v70, v102
	v_sub_f32_e32 v73, v73, v102
	v_sub_f32_e32 v72, v72, v102
	v_mov_b32_e32 v102, v103
	v_pk_mul_f32 v[72:73], v[102:103], v[72:73]
	v_pk_mul_f32 v[70:71], v[104:105], v[70:71]
	s_and_b64 vcc, exec, s[42:43]
	s_waitcnt lgkmcnt(0)
	v_pk_fma_f32 v[70:71], v[70:71], v[82:83], v[86:87]
	v_pk_fma_f32 v[72:73], v[72:73], v[84:85], v[88:89]
	v_cndmask_b32_e64 v71, v215, v71, s[40:41]
	v_cndmask_b32_e64 v73, v215, v73, s[40:41]
	v_cndmask_b32_e64 v72, v215, v72, s[40:41]
	v_cndmask_b32_e64 v70, v215, v70, s[40:41]
	global_store_dwordx4 v[98:99], v[70:73], off offset:576
	s_cbranch_vccnz .LBB0_244
	v_add_co_u32_e32 v82, vcc, 0x1000, v130
	s_nop 1
	v_addc_co_u32_e32 v83, vcc, 0, v131, vcc
	ds_read_b128 v[82:85], v166 offset:20032
	s_nop 0
	ds_read_b128 v[86:89], v166 offset:19008
	s_waitcnt lgkmcnt(0)
	v_pk_add_f32 v[84:85], v[84:85], 1.0 op_sel_hi:[1,0]
	v_pk_add_f32 v[82:83], v[82:83], 1.0 op_sel_hi:[1,0]
	s_waitcnt lgkmcnt(0)
	v_pk_fma_f32 v[72:73], v[72:73], v[84:85], v[88:89]
	v_pk_fma_f32 v[70:71], v[70:71], v[82:83], v[86:87]
	s_nop 0
	v_cvt_pk_bf16_f32 v70, v70, v71
	v_cvt_pk_bf16_f32 v71, v72, v73
	global_store_dwordx2 v[100:101], v[70:71], off offset:288
.LBB0_244:
	v_lshl_add_u64 v[82:83], v[98:99], 0, s[14:15]
	v_lshl_add_u64 v[84:85], v[100:101], 0, s[0:1]
	ds_read_b128 v[70:73], v166 offset:16384
	ds_read_b128 v[94:97], v166 offset:17408
	ds_read_b64 v[86:87], v0 offset:8576
	s_and_b64 vcc, exec, s[42:43]
	s_waitcnt lgkmcnt(0)
	v_sub_f32_e32 v89, v91, v86
	v_sub_f32_e32 v88, v90, v86
	v_sub_f32_e32 v91, v93, v86
	v_sub_f32_e32 v90, v92, v86
	v_pk_mul_f32 v[90:91], v[86:87], v[90:91] op_sel:[1,0]
	v_pk_mul_f32 v[88:89], v[86:87], v[88:89] op_sel:[1,0]
	s_waitcnt lgkmcnt(0)
	v_pk_fma_f32 v[72:73], v[72:73], v[90:91], v[96:97]
	v_pk_fma_f32 v[70:71], v[70:71], v[88:89], v[94:95]
	v_cndmask_b32_e64 v73, v215, v73, s[40:41]
	v_cndmask_b32_e64 v72, v215, v72, s[40:41]
	v_cndmask_b32_e64 v71, v215, v71, s[40:41]
	v_cndmask_b32_e64 v70, v215, v70, s[40:41]
	global_store_dwordx4 v[82:83], v[70:73], off
	s_cbranch_vccnz .LBB0_246
	ds_read_b128 v[88:91], v166 offset:19456
	ds_read_b128 v[92:95], v166 offset:18432
	s_waitcnt lgkmcnt(0)
	v_pk_add_f32 v[90:91], v[90:91], 1.0 op_sel_hi:[1,0]
	v_pk_add_f32 v[88:89], v[88:89], 1.0 op_sel_hi:[1,0]
	s_waitcnt lgkmcnt(0)
	v_pk_fma_f32 v[72:73], v[72:73], v[90:91], v[94:95]
	v_pk_fma_f32 v[70:71], v[70:71], v[88:89], v[92:93]
	s_nop 0
	v_cvt_pk_bf16_f32 v70, v70, v71
	v_cvt_pk_bf16_f32 v71, v72, v73
	global_store_dwordx2 v[84:85], v[70:71], off
.LBB0_246:
	ds_read_b128 v[70:73], v166 offset:16448
	ds_read_b128 v[90:93], v166 offset:17472
	v_mov_b32_e32 v88, v87
	v_mov_b32_e32 v89, v87
	v_sub_f32_e32 v95, v79, v86
	v_sub_f32_e32 v94, v78, v86
	v_sub_f32_e32 v81, v81, v86
	v_sub_f32_e32 v80, v80, v86
	v_mov_b32_e32 v78, v87
	v_mov_b32_e32 v79, v87
	v_pk_mul_f32 v[80:81], v[78:79], v[80:81]
	v_pk_mul_f32 v[94:95], v[88:89], v[94:95]
	s_and_b64 vcc, exec, s[42:43]
	s_waitcnt lgkmcnt(0)
	v_pk_fma_f32 v[70:71], v[94:95], v[70:71], v[90:91]
	v_pk_fma_f32 v[72:73], v[80:81], v[72:73], v[92:93]
	v_cndmask_b32_e64 v71, v215, v71, s[40:41]
	v_cndmask_b32_e64 v73, v215, v73, s[40:41]
	v_cndmask_b32_e64 v72, v215, v72, s[40:41]
	v_cndmask_b32_e64 v70, v215, v70, s[40:41]
	global_store_dwordx4 v[82:83], v[70:73], off offset:64
	s_cbranch_vccnz .LBB0_248
	v_add_co_u32_e32 v80, vcc, 0x1000, v130
	s_nop 1
	v_addc_co_u32_e32 v81, vcc, 0, v131, vcc
	ds_read_b128 v[90:93], v166 offset:19520
	ds_read_b128 v[94:97], v166 offset:18496
	s_waitcnt lgkmcnt(0)
	v_pk_add_f32 v[80:81], v[92:93], 1.0 op_sel_hi:[1,0]
	v_pk_add_f32 v[90:91], v[90:91], 1.0 op_sel_hi:[1,0]
	s_waitcnt lgkmcnt(0)
	v_pk_fma_f32 v[72:73], v[72:73], v[80:81], v[96:97]
	v_pk_fma_f32 v[70:71], v[70:71], v[90:91], v[94:95]
	s_nop 0
	v_cvt_pk_bf16_f32 v70, v70, v71
	v_cvt_pk_bf16_f32 v71, v72, v73
	global_store_dwordx2 v[84:85], v[70:71], off offset:32
.LBB0_248:
	ds_read_b128 v[70:73], v166 offset:16896
	ds_read_b128 v[90:93], v166 offset:17920
	v_sub_f32_e32 v67, v67, v86
	v_sub_f32_e32 v66, v66, v86
	v_sub_f32_e32 v69, v69, v86
	v_sub_f32_e32 v68, v68, v86
	v_pk_mul_f32 v[68:69], v[78:79], v[68:69]
	v_pk_mul_f32 v[66:67], v[88:89], v[66:67]
	s_and_b64 vcc, exec, s[42:43]
	s_waitcnt lgkmcnt(0)
	v_pk_fma_f32 v[66:67], v[66:67], v[70:71], v[90:91]
	v_pk_fma_f32 v[68:69], v[68:69], v[72:73], v[92:93]
	v_cndmask_b32_e64 v67, v215, v67, s[40:41]
	v_cndmask_b32_e64 v69, v215, v69, s[40:41]
	v_cndmask_b32_e64 v68, v215, v68, s[40:41]
	v_cndmask_b32_e64 v66, v215, v66, s[40:41]
	global_store_dwordx4 v[82:83], v[66:69], off offset:512
	s_cbranch_vccnz .LBB0_250
	v_add_co_u32_e32 v70, vcc, 0x1000, v130
	s_nop 1
	v_addc_co_u32_e32 v71, vcc, 0, v131, vcc
	ds_read_b128 v[70:73], v166 offset:19968
	s_nop 0
	ds_read_b128 v[78:81], v166 offset:18944
	s_waitcnt lgkmcnt(0)
	v_pk_add_f32 v[72:73], v[72:73], 1.0 op_sel_hi:[1,0]
	v_pk_add_f32 v[70:71], v[70:71], 1.0 op_sel_hi:[1,0]
	s_waitcnt lgkmcnt(0)
	v_pk_fma_f32 v[68:69], v[68:69], v[72:73], v[80:81]
	v_pk_fma_f32 v[66:67], v[66:67], v[70:71], v[78:79]
	s_nop 0
	v_cvt_pk_bf16_f32 v66, v66, v67
	v_cvt_pk_bf16_f32 v67, v68, v69
	global_store_dwordx2 v[84:85], v[66:67], off offset:256
.LBB0_250:
	ds_read_b128 v[66:69], v166 offset:16960
	ds_read_b128 v[70:73], v166 offset:17984
	v_sub_f32_e32 v55, v55, v86
	v_sub_f32_e32 v54, v54, v86
	v_sub_f32_e32 v57, v57, v86
	v_sub_f32_e32 v56, v56, v86
	v_mov_b32_e32 v86, v87
	v_pk_mul_f32 v[56:57], v[86:87], v[56:57]
	v_pk_mul_f32 v[54:55], v[88:89], v[54:55]
	s_and_b64 vcc, exec, s[42:43]
	s_waitcnt lgkmcnt(0)
	v_pk_fma_f32 v[54:55], v[54:55], v[66:67], v[70:71]
	v_pk_fma_f32 v[56:57], v[56:57], v[68:69], v[72:73]
	v_cndmask_b32_e64 v55, v215, v55, s[40:41]
	v_cndmask_b32_e64 v57, v215, v57, s[40:41]
	v_cndmask_b32_e64 v56, v215, v56, s[40:41]
	v_cndmask_b32_e64 v54, v215, v54, s[40:41]
	global_store_dwordx4 v[82:83], v[54:57], off offset:576
	s_cbranch_vccnz .LBB0_252
	v_add_co_u32_e32 v66, vcc, 0x1000, v130
	s_nop 1
	v_addc_co_u32_e32 v67, vcc, 0, v131, vcc
	ds_read_b128 v[66:69], v166 offset:20032
	s_nop 0
	ds_read_b128 v[70:73], v166 offset:19008
	s_waitcnt lgkmcnt(0)
	v_pk_add_f32 v[68:69], v[68:69], 1.0 op_sel_hi:[1,0]
	v_pk_add_f32 v[66:67], v[66:67], 1.0 op_sel_hi:[1,0]
	s_waitcnt lgkmcnt(0)
	v_pk_fma_f32 v[56:57], v[56:57], v[68:69], v[72:73]
	v_pk_fma_f32 v[54:55], v[54:55], v[66:67], v[70:71]
	s_nop 0
	v_cvt_pk_bf16_f32 v54, v54, v55
	v_cvt_pk_bf16_f32 v55, v56, v57
	global_store_dwordx2 v[84:85], v[54:55], off offset:288
.LBB0_252:
	s_mov_b64 s[0:1], 0x28000
	v_lshl_add_u64 v[66:67], v[82:83], 0, s[16:17]
	v_lshl_add_u64 v[68:69], v[84:85], 0, s[0:1]
	ds_read_b128 v[54:57], v166 offset:16384
	ds_read_b128 v[78:81], v166 offset:17408
	ds_read_b64 v[70:71], v0 offset:9216
	s_and_b64 vcc, exec, s[42:43]
	s_waitcnt lgkmcnt(0)
	v_sub_f32_e32 v73, v75, v70
	v_sub_f32_e32 v72, v74, v70
	v_sub_f32_e32 v75, v77, v70
	v_sub_f32_e32 v74, v76, v70
	v_pk_mul_f32 v[74:75], v[70:71], v[74:75] op_sel:[1,0]
	v_pk_mul_f32 v[72:73], v[70:71], v[72:73] op_sel:[1,0]
	s_waitcnt lgkmcnt(0)
	v_pk_fma_f32 v[56:57], v[56:57], v[74:75], v[80:81]
	v_pk_fma_f32 v[54:55], v[54:55], v[72:73], v[78:79]
	v_cndmask_b32_e64 v57, v215, v57, s[40:41]
	v_cndmask_b32_e64 v56, v215, v56, s[40:41]
	v_cndmask_b32_e64 v55, v215, v55, s[40:41]
	v_cndmask_b32_e64 v54, v215, v54, s[40:41]
	global_store_dwordx4 v[66:67], v[54:57], off
	s_cbranch_vccnz .LBB0_254
	ds_read_b128 v[72:75], v166 offset:19456
	ds_read_b128 v[76:79], v166 offset:18432
	s_waitcnt lgkmcnt(0)
	v_pk_add_f32 v[74:75], v[74:75], 1.0 op_sel_hi:[1,0]
	v_pk_add_f32 v[72:73], v[72:73], 1.0 op_sel_hi:[1,0]
	s_waitcnt lgkmcnt(0)
	v_pk_fma_f32 v[56:57], v[56:57], v[74:75], v[78:79]
	v_pk_fma_f32 v[54:55], v[54:55], v[72:73], v[76:77]
	s_nop 0
	v_cvt_pk_bf16_f32 v54, v54, v55
	v_cvt_pk_bf16_f32 v55, v56, v57
	global_store_dwordx2 v[68:69], v[54:55], off
.LBB0_254:
	ds_read_b128 v[54:57], v166 offset:16448
	ds_read_b128 v[74:77], v166 offset:17472
	v_mov_b32_e32 v72, v71
	v_mov_b32_e32 v73, v71
	v_sub_f32_e32 v79, v63, v70
	v_sub_f32_e32 v78, v62, v70
	v_sub_f32_e32 v65, v65, v70
	v_sub_f32_e32 v64, v64, v70
	v_mov_b32_e32 v62, v71
	v_mov_b32_e32 v63, v71
	v_pk_mul_f32 v[64:65], v[62:63], v[64:65]
	v_pk_mul_f32 v[78:79], v[72:73], v[78:79]
	s_and_b64 vcc, exec, s[42:43]
	s_waitcnt lgkmcnt(0)
	v_pk_fma_f32 v[54:55], v[78:79], v[54:55], v[74:75]
	v_pk_fma_f32 v[56:57], v[64:65], v[56:57], v[76:77]
	v_cndmask_b32_e64 v55, v215, v55, s[40:41]
	v_cndmask_b32_e64 v57, v215, v57, s[40:41]
	v_cndmask_b32_e64 v56, v215, v56, s[40:41]
	v_cndmask_b32_e64 v54, v215, v54, s[40:41]
	global_store_dwordx4 v[66:67], v[54:57], off offset:64
	s_cbranch_vccnz .LBB0_256
	v_add_co_u32_e32 v64, vcc, 0x1000, v130
	s_nop 1
	v_addc_co_u32_e32 v65, vcc, 0, v131, vcc
	ds_read_b128 v[74:77], v166 offset:19520
	ds_read_b128 v[78:81], v166 offset:18496
	s_waitcnt lgkmcnt(0)
	v_pk_add_f32 v[64:65], v[76:77], 1.0 op_sel_hi:[1,0]
	v_pk_add_f32 v[74:75], v[74:75], 1.0 op_sel_hi:[1,0]
	s_waitcnt lgkmcnt(0)
	v_pk_fma_f32 v[56:57], v[56:57], v[64:65], v[80:81]
	v_pk_fma_f32 v[54:55], v[54:55], v[74:75], v[78:79]
	s_nop 0
	v_cvt_pk_bf16_f32 v54, v54, v55
	v_cvt_pk_bf16_f32 v55, v56, v57
	global_store_dwordx2 v[68:69], v[54:55], off offset:32
.LBB0_256:
	ds_read_b128 v[54:57], v166 offset:16896
	ds_read_b128 v[74:77], v166 offset:17920
	v_sub_f32_e32 v51, v51, v70
	v_sub_f32_e32 v50, v50, v70
	v_sub_f32_e32 v53, v53, v70
	v_sub_f32_e32 v52, v52, v70
	v_pk_mul_f32 v[52:53], v[62:63], v[52:53]
	v_pk_mul_f32 v[50:51], v[72:73], v[50:51]
	s_and_b64 vcc, exec, s[42:43]
	s_waitcnt lgkmcnt(0)
	v_pk_fma_f32 v[50:51], v[50:51], v[54:55], v[74:75]
	v_pk_fma_f32 v[52:53], v[52:53], v[56:57], v[76:77]
	v_cndmask_b32_e64 v51, v215, v51, s[40:41]
	v_cndmask_b32_e64 v53, v215, v53, s[40:41]
	v_cndmask_b32_e64 v52, v215, v52, s[40:41]
	v_cndmask_b32_e64 v50, v215, v50, s[40:41]
	global_store_dwordx4 v[66:67], v[50:53], off offset:512
	s_cbranch_vccnz .LBB0_258
	v_add_co_u32_e32 v54, vcc, 0x1000, v130
	s_nop 1
	v_addc_co_u32_e32 v55, vcc, 0, v131, vcc
	ds_read_b128 v[54:57], v166 offset:19968
	s_nop 0
	ds_read_b128 v[62:65], v166 offset:18944
	s_waitcnt lgkmcnt(0)
	v_pk_add_f32 v[56:57], v[56:57], 1.0 op_sel_hi:[1,0]
	v_pk_add_f32 v[54:55], v[54:55], 1.0 op_sel_hi:[1,0]
	s_waitcnt lgkmcnt(0)
	v_pk_fma_f32 v[52:53], v[52:53], v[56:57], v[64:65]
	v_pk_fma_f32 v[50:51], v[50:51], v[54:55], v[62:63]
	s_nop 0
	v_cvt_pk_bf16_f32 v50, v50, v51
	v_cvt_pk_bf16_f32 v51, v52, v53
	global_store_dwordx2 v[68:69], v[50:51], off offset:256
.LBB0_258:
	ds_read_b128 v[50:53], v166 offset:16960
	ds_read_b128 v[54:57], v166 offset:17984
	v_sub_f32_e32 v39, v39, v70
	v_sub_f32_e32 v38, v38, v70
	v_sub_f32_e32 v41, v41, v70
	v_sub_f32_e32 v40, v40, v70
	v_mov_b32_e32 v70, v71
	v_pk_mul_f32 v[40:41], v[70:71], v[40:41]
	v_pk_mul_f32 v[38:39], v[72:73], v[38:39]
	s_and_b64 vcc, exec, s[42:43]
	s_waitcnt lgkmcnt(0)
	v_pk_fma_f32 v[38:39], v[38:39], v[50:51], v[54:55]
	v_pk_fma_f32 v[40:41], v[40:41], v[52:53], v[56:57]
	v_cndmask_b32_e64 v39, v215, v39, s[40:41]
	v_cndmask_b32_e64 v41, v215, v41, s[40:41]
	v_cndmask_b32_e64 v40, v215, v40, s[40:41]
	v_cndmask_b32_e64 v38, v215, v38, s[40:41]
	global_store_dwordx4 v[66:67], v[38:41], off offset:576
	s_cbranch_vccnz .LBB0_260
	v_add_co_u32_e32 v50, vcc, 0x1000, v130
	s_nop 1
	v_addc_co_u32_e32 v51, vcc, 0, v131, vcc
	ds_read_b128 v[50:53], v166 offset:20032
	s_nop 0
	ds_read_b128 v[54:57], v166 offset:19008
	s_waitcnt lgkmcnt(0)
	v_pk_add_f32 v[52:53], v[52:53], 1.0 op_sel_hi:[1,0]
	v_pk_add_f32 v[50:51], v[50:51], 1.0 op_sel_hi:[1,0]
	s_waitcnt lgkmcnt(0)
	v_pk_fma_f32 v[40:41], v[40:41], v[52:53], v[56:57]
	v_pk_fma_f32 v[38:39], v[38:39], v[50:51], v[54:55]
	s_nop 0
	v_cvt_pk_bf16_f32 v38, v38, v39
	v_cvt_pk_bf16_f32 v39, v40, v41
	global_store_dwordx2 v[68:69], v[38:39], off offset:288
.LBB0_260:
	s_mov_b64 s[0:1], 0x8000
	v_lshl_add_u64 v[50:51], v[66:67], 0, s[14:15]
	v_lshl_add_u64 v[52:53], v[68:69], 0, s[0:1]
	ds_read_b128 v[38:41], v166 offset:16384
	ds_read_b128 v[62:65], v166 offset:17408
	ds_read_b64 v[54:55], v0 offset:9344
	s_and_b64 vcc, exec, s[42:43]
	s_waitcnt lgkmcnt(0)
	v_sub_f32_e32 v57, v59, v54
	v_sub_f32_e32 v56, v58, v54
	v_sub_f32_e32 v59, v61, v54
	v_sub_f32_e32 v58, v60, v54
	v_pk_mul_f32 v[58:59], v[54:55], v[58:59] op_sel:[1,0]
	v_pk_mul_f32 v[56:57], v[54:55], v[56:57] op_sel:[1,0]
	s_waitcnt lgkmcnt(0)
	v_pk_fma_f32 v[40:41], v[40:41], v[58:59], v[64:65]
	v_pk_fma_f32 v[38:39], v[38:39], v[56:57], v[62:63]
	v_cndmask_b32_e64 v41, v215, v41, s[40:41]
	v_cndmask_b32_e64 v40, v215, v40, s[40:41]
	v_cndmask_b32_e64 v39, v215, v39, s[40:41]
	v_cndmask_b32_e64 v38, v215, v38, s[40:41]
	global_store_dwordx4 v[50:51], v[38:41], off
	s_cbranch_vccnz .LBB0_262
	ds_read_b128 v[56:59], v166 offset:19456
	ds_read_b128 v[60:63], v166 offset:18432
	s_waitcnt lgkmcnt(0)
	v_pk_add_f32 v[58:59], v[58:59], 1.0 op_sel_hi:[1,0]
	v_pk_add_f32 v[56:57], v[56:57], 1.0 op_sel_hi:[1,0]
	s_waitcnt lgkmcnt(0)
	v_pk_fma_f32 v[40:41], v[40:41], v[58:59], v[62:63]
	v_pk_fma_f32 v[38:39], v[38:39], v[56:57], v[60:61]
	s_nop 0
	v_cvt_pk_bf16_f32 v38, v38, v39
	v_cvt_pk_bf16_f32 v39, v40, v41
	global_store_dwordx2 v[52:53], v[38:39], off
.LBB0_262:
	ds_read_b128 v[38:41], v166 offset:16448
	ds_read_b128 v[58:61], v166 offset:17472
	v_mov_b32_e32 v56, v55
	v_mov_b32_e32 v57, v55
	v_sub_f32_e32 v63, v47, v54
	v_sub_f32_e32 v62, v46, v54
	v_sub_f32_e32 v49, v49, v54
	v_sub_f32_e32 v48, v48, v54
	v_mov_b32_e32 v46, v55
	v_mov_b32_e32 v47, v55
	v_pk_mul_f32 v[48:49], v[46:47], v[48:49]
	v_pk_mul_f32 v[62:63], v[56:57], v[62:63]
	s_and_b64 vcc, exec, s[42:43]
	s_waitcnt lgkmcnt(0)
	v_pk_fma_f32 v[38:39], v[62:63], v[38:39], v[58:59]
	v_pk_fma_f32 v[40:41], v[48:49], v[40:41], v[60:61]
	v_cndmask_b32_e64 v39, v215, v39, s[40:41]
	v_cndmask_b32_e64 v41, v215, v41, s[40:41]
	v_cndmask_b32_e64 v40, v215, v40, s[40:41]
	v_cndmask_b32_e64 v38, v215, v38, s[40:41]
	global_store_dwordx4 v[50:51], v[38:41], off offset:64
	s_cbranch_vccnz .LBB0_264
	v_add_co_u32_e32 v48, vcc, 0x1000, v130
	s_nop 1
	v_addc_co_u32_e32 v49, vcc, 0, v131, vcc
	ds_read_b128 v[58:61], v166 offset:19520
	ds_read_b128 v[62:65], v166 offset:18496
	s_waitcnt lgkmcnt(0)
	v_pk_add_f32 v[48:49], v[60:61], 1.0 op_sel_hi:[1,0]
	v_pk_add_f32 v[58:59], v[58:59], 1.0 op_sel_hi:[1,0]
	s_waitcnt lgkmcnt(0)
	v_pk_fma_f32 v[40:41], v[40:41], v[48:49], v[64:65]
	v_pk_fma_f32 v[38:39], v[38:39], v[58:59], v[62:63]
	s_nop 0
	v_cvt_pk_bf16_f32 v38, v38, v39
	v_cvt_pk_bf16_f32 v39, v40, v41
	global_store_dwordx2 v[52:53], v[38:39], off offset:32
.LBB0_264:
	ds_read_b128 v[38:41], v166 offset:16896
	ds_read_b128 v[58:61], v166 offset:17920
	v_sub_f32_e32 v35, v35, v54
	v_sub_f32_e32 v34, v34, v54
	v_sub_f32_e32 v37, v37, v54
	v_sub_f32_e32 v36, v36, v54
	v_pk_mul_f32 v[36:37], v[46:47], v[36:37]
	v_pk_mul_f32 v[34:35], v[56:57], v[34:35]
	s_and_b64 vcc, exec, s[42:43]
	s_waitcnt lgkmcnt(0)
	v_pk_fma_f32 v[34:35], v[34:35], v[38:39], v[58:59]
	v_pk_fma_f32 v[36:37], v[36:37], v[40:41], v[60:61]
	v_cndmask_b32_e64 v35, v215, v35, s[40:41]
	v_cndmask_b32_e64 v37, v215, v37, s[40:41]
	v_cndmask_b32_e64 v36, v215, v36, s[40:41]
	v_cndmask_b32_e64 v34, v215, v34, s[40:41]
	global_store_dwordx4 v[50:51], v[34:37], off offset:512
	s_cbranch_vccnz .LBB0_266
	v_add_co_u32_e32 v38, vcc, 0x1000, v130
	s_nop 1
	v_addc_co_u32_e32 v39, vcc, 0, v131, vcc
	ds_read_b128 v[38:41], v166 offset:19968
	s_nop 0
	ds_read_b128 v[46:49], v166 offset:18944
	s_waitcnt lgkmcnt(0)
	v_pk_add_f32 v[40:41], v[40:41], 1.0 op_sel_hi:[1,0]
	v_pk_add_f32 v[38:39], v[38:39], 1.0 op_sel_hi:[1,0]
	s_waitcnt lgkmcnt(0)
	v_pk_fma_f32 v[36:37], v[36:37], v[40:41], v[48:49]
	v_pk_fma_f32 v[34:35], v[34:35], v[38:39], v[46:47]
	s_nop 0
	v_cvt_pk_bf16_f32 v34, v34, v35
	v_cvt_pk_bf16_f32 v35, v36, v37
	global_store_dwordx2 v[52:53], v[34:35], off offset:256
.LBB0_266:
	ds_read_b128 v[34:37], v166 offset:16960
	ds_read_b128 v[38:41], v166 offset:17984
	v_sub_f32_e32 v27, v27, v54
	v_sub_f32_e32 v26, v26, v54
	v_sub_f32_e32 v29, v29, v54
	v_sub_f32_e32 v28, v28, v54
	v_mov_b32_e32 v54, v55
	v_pk_mul_f32 v[28:29], v[54:55], v[28:29]
	v_pk_mul_f32 v[26:27], v[56:57], v[26:27]
	s_and_b64 vcc, exec, s[42:43]
	s_waitcnt lgkmcnt(0)
	v_pk_fma_f32 v[26:27], v[26:27], v[34:35], v[38:39]
	v_pk_fma_f32 v[28:29], v[28:29], v[36:37], v[40:41]
	v_cndmask_b32_e64 v27, v215, v27, s[40:41]
	v_cndmask_b32_e64 v29, v215, v29, s[40:41]
	v_cndmask_b32_e64 v28, v215, v28, s[40:41]
	v_cndmask_b32_e64 v26, v215, v26, s[40:41]
	global_store_dwordx4 v[50:51], v[26:29], off offset:576
	s_cbranch_vccnz .LBB0_268
	v_add_co_u32_e32 v34, vcc, 0x1000, v130
	s_nop 1
	v_addc_co_u32_e32 v35, vcc, 0, v131, vcc
	ds_read_b128 v[34:37], v166 offset:20032
	s_nop 0
	ds_read_b128 v[38:41], v166 offset:19008
	s_waitcnt lgkmcnt(0)
	v_pk_add_f32 v[36:37], v[36:37], 1.0 op_sel_hi:[1,0]
	v_pk_add_f32 v[34:35], v[34:35], 1.0 op_sel_hi:[1,0]
	s_waitcnt lgkmcnt(0)
	v_pk_fma_f32 v[28:29], v[28:29], v[36:37], v[40:41]
	v_pk_fma_f32 v[26:27], v[26:27], v[34:35], v[38:39]
	s_nop 0
	v_cvt_pk_bf16_f32 v26, v26, v27
	v_cvt_pk_bf16_f32 v27, v28, v29
	global_store_dwordx2 v[52:53], v[26:27], off offset:288
.LBB0_268:
	v_lshl_add_u64 v[34:35], v[50:51], 0, s[14:15]
	v_lshl_add_u64 v[36:37], v[52:53], 0, s[0:1]
	ds_read_b128 v[26:29], v166 offset:16384
	ds_read_b128 v[46:49], v166 offset:17408
	ds_read_b64 v[38:39], v0 offset:9472
	s_and_b64 vcc, exec, s[42:43]
	s_waitcnt lgkmcnt(0)
	v_sub_f32_e32 v41, v43, v38
	v_sub_f32_e32 v40, v42, v38
	v_sub_f32_e32 v43, v45, v38
	v_sub_f32_e32 v42, v44, v38
	v_pk_mul_f32 v[42:43], v[38:39], v[42:43] op_sel:[1,0]
	v_pk_mul_f32 v[40:41], v[38:39], v[40:41] op_sel:[1,0]
	s_waitcnt lgkmcnt(0)
	v_pk_fma_f32 v[28:29], v[28:29], v[42:43], v[48:49]
	v_pk_fma_f32 v[26:27], v[26:27], v[40:41], v[46:47]
	v_cndmask_b32_e64 v29, v215, v29, s[40:41]
	v_cndmask_b32_e64 v28, v215, v28, s[40:41]
	v_cndmask_b32_e64 v27, v215, v27, s[40:41]
	v_cndmask_b32_e64 v26, v215, v26, s[40:41]
	global_store_dwordx4 v[34:35], v[26:29], off
	s_cbranch_vccnz .LBB0_270
	ds_read_b128 v[40:43], v166 offset:19456
	ds_read_b128 v[44:47], v166 offset:18432
	s_waitcnt lgkmcnt(0)
	v_pk_add_f32 v[42:43], v[42:43], 1.0 op_sel_hi:[1,0]
	v_pk_add_f32 v[40:41], v[40:41], 1.0 op_sel_hi:[1,0]
	s_waitcnt lgkmcnt(0)
	v_pk_fma_f32 v[28:29], v[28:29], v[42:43], v[46:47]
	v_pk_fma_f32 v[26:27], v[26:27], v[40:41], v[44:45]
	s_nop 0
	v_cvt_pk_bf16_f32 v26, v26, v27
	v_cvt_pk_bf16_f32 v27, v28, v29
	global_store_dwordx2 v[36:37], v[26:27], off
.LBB0_270:
	ds_read_b128 v[26:29], v166 offset:16448
	ds_read_b128 v[42:45], v166 offset:17472
	v_mov_b32_e32 v40, v39
	v_mov_b32_e32 v41, v39
	v_sub_f32_e32 v47, v31, v38
	v_sub_f32_e32 v46, v30, v38
	v_sub_f32_e32 v33, v33, v38
	v_sub_f32_e32 v32, v32, v38
	v_mov_b32_e32 v30, v39
	v_mov_b32_e32 v31, v39
	v_pk_mul_f32 v[32:33], v[30:31], v[32:33]
	v_pk_mul_f32 v[46:47], v[40:41], v[46:47]
	s_and_b64 vcc, exec, s[42:43]
	s_waitcnt lgkmcnt(0)
	v_pk_fma_f32 v[26:27], v[46:47], v[26:27], v[42:43]
	v_pk_fma_f32 v[28:29], v[32:33], v[28:29], v[44:45]
	v_cndmask_b32_e64 v27, v215, v27, s[40:41]
	v_cndmask_b32_e64 v29, v215, v29, s[40:41]
	v_cndmask_b32_e64 v28, v215, v28, s[40:41]
	v_cndmask_b32_e64 v26, v215, v26, s[40:41]
	global_store_dwordx4 v[34:35], v[26:29], off offset:64
	s_cbranch_vccnz .LBB0_272
	v_add_co_u32_e32 v32, vcc, 0x1000, v130
	s_nop 1
	v_addc_co_u32_e32 v33, vcc, 0, v131, vcc
	ds_read_b128 v[42:45], v166 offset:19520
	ds_read_b128 v[46:49], v166 offset:18496
	s_waitcnt lgkmcnt(0)
	v_pk_add_f32 v[32:33], v[44:45], 1.0 op_sel_hi:[1,0]
	v_pk_add_f32 v[42:43], v[42:43], 1.0 op_sel_hi:[1,0]
	s_waitcnt lgkmcnt(0)
	v_pk_fma_f32 v[28:29], v[28:29], v[32:33], v[48:49]
	v_pk_fma_f32 v[26:27], v[26:27], v[42:43], v[46:47]
	s_nop 0
	v_cvt_pk_bf16_f32 v26, v26, v27
	v_cvt_pk_bf16_f32 v27, v28, v29
	global_store_dwordx2 v[36:37], v[26:27], off offset:32
.LBB0_272:
	ds_read_b128 v[26:29], v166 offset:16896
	ds_read_b128 v[42:45], v166 offset:17920
	v_sub_f32_e32 v23, v23, v38
	v_sub_f32_e32 v22, v22, v38
	v_sub_f32_e32 v25, v25, v38
	v_sub_f32_e32 v24, v24, v38
	v_pk_mul_f32 v[24:25], v[30:31], v[24:25]
	v_pk_mul_f32 v[22:23], v[40:41], v[22:23]
	s_and_b64 vcc, exec, s[42:43]
	s_waitcnt lgkmcnt(0)
	v_pk_fma_f32 v[22:23], v[22:23], v[26:27], v[42:43]
	v_pk_fma_f32 v[24:25], v[24:25], v[28:29], v[44:45]
	v_cndmask_b32_e64 v23, v215, v23, s[40:41]
	v_cndmask_b32_e64 v25, v215, v25, s[40:41]
	v_cndmask_b32_e64 v24, v215, v24, s[40:41]
	v_cndmask_b32_e64 v22, v215, v22, s[40:41]
	global_store_dwordx4 v[34:35], v[22:25], off offset:512
	s_cbranch_vccnz .LBB0_274
	v_add_co_u32_e32 v26, vcc, 0x1000, v130
	s_nop 1
	v_addc_co_u32_e32 v27, vcc, 0, v131, vcc
	ds_read_b128 v[26:29], v166 offset:19968
	s_nop 0
	ds_read_b128 v[30:33], v166 offset:18944
	s_waitcnt lgkmcnt(0)
	v_pk_add_f32 v[28:29], v[28:29], 1.0 op_sel_hi:[1,0]
	v_pk_add_f32 v[26:27], v[26:27], 1.0 op_sel_hi:[1,0]
	s_waitcnt lgkmcnt(0)
	v_pk_fma_f32 v[24:25], v[24:25], v[28:29], v[32:33]
	v_pk_fma_f32 v[22:23], v[22:23], v[26:27], v[30:31]
	s_nop 0
	v_cvt_pk_bf16_f32 v22, v22, v23
	v_cvt_pk_bf16_f32 v23, v24, v25
	global_store_dwordx2 v[36:37], v[22:23], off offset:256
.LBB0_274:
	ds_read_b128 v[22:25], v166 offset:16960
	ds_read_b128 v[26:29], v166 offset:17984
	v_sub_f32_e32 v19, v19, v38
	v_sub_f32_e32 v18, v18, v38
	v_sub_f32_e32 v21, v21, v38
	v_sub_f32_e32 v20, v20, v38
	v_mov_b32_e32 v38, v39
	v_pk_mul_f32 v[20:21], v[38:39], v[20:21]
	v_pk_mul_f32 v[18:19], v[40:41], v[18:19]
	s_and_b64 vcc, exec, s[42:43]
	s_waitcnt lgkmcnt(0)
	v_pk_fma_f32 v[18:19], v[18:19], v[22:23], v[26:27]
	v_pk_fma_f32 v[20:21], v[20:21], v[24:25], v[28:29]
	v_cndmask_b32_e64 v19, v215, v19, s[40:41]
	v_cndmask_b32_e64 v21, v215, v21, s[40:41]
	v_cndmask_b32_e64 v20, v215, v20, s[40:41]
	v_cndmask_b32_e64 v18, v215, v18, s[40:41]
	global_store_dwordx4 v[34:35], v[18:21], off offset:576
	s_cbranch_vccnz .LBB0_276
	v_add_co_u32_e32 v22, vcc, 0x1000, v130
	s_nop 1
	v_addc_co_u32_e32 v23, vcc, 0, v131, vcc
	ds_read_b128 v[22:25], v166 offset:20032
	s_nop 0
	ds_read_b128 v[26:29], v166 offset:19008
	s_waitcnt lgkmcnt(0)
	v_pk_add_f32 v[24:25], v[24:25], 1.0 op_sel_hi:[1,0]
	v_pk_add_f32 v[22:23], v[22:23], 1.0 op_sel_hi:[1,0]
	s_waitcnt lgkmcnt(0)
	v_pk_fma_f32 v[20:21], v[20:21], v[24:25], v[28:29]
	v_pk_fma_f32 v[18:19], v[18:19], v[22:23], v[26:27]
	s_nop 0
	v_cvt_pk_bf16_f32 v18, v18, v19
	v_cvt_pk_bf16_f32 v19, v20, v21
	global_store_dwordx2 v[36:37], v[18:19], off offset:288
.LBB0_276:
	s_nop 0
	v_lshl_add_u64 v[18:19], v[34:35], 0, s[14:15]
	v_lshl_add_u64 v[20:21], v[36:37], 0, s[0:1]
	ds_read_b128 v[24:27], v166 offset:16384
	ds_read_b128 v[28:31], v166 offset:17408
	ds_read_b64 v[22:23], v0 offset:9600
	s_and_b64 vcc, exec, s[42:43]
	s_waitcnt lgkmcnt(0)
	v_sub_f32_e32 v15, v15, v22
	v_sub_f32_e32 v14, v14, v22
	v_sub_f32_e32 v17, v17, v22
	v_sub_f32_e32 v16, v16, v22
	v_pk_mul_f32 v[16:17], v[22:23], v[16:17] op_sel:[1,0]
	v_pk_mul_f32 v[14:15], v[22:23], v[14:15] op_sel:[1,0]
	s_waitcnt lgkmcnt(0)
	v_pk_fma_f32 v[16:17], v[26:27], v[16:17], v[30:31]
	v_pk_fma_f32 v[14:15], v[24:25], v[14:15], v[28:29]
	v_cndmask_b32_e64 v17, v215, v17, s[40:41]
	v_cndmask_b32_e64 v16, v215, v16, s[40:41]
	v_cndmask_b32_e64 v15, v215, v15, s[40:41]
	v_cndmask_b32_e64 v14, v215, v14, s[40:41]
	global_store_dwordx4 v[18:19], v[14:17], off
	s_cbranch_vccnz .LBB0_278
	ds_read_b128 v[24:27], v166 offset:19456
	ds_read_b128 v[28:31], v166 offset:18432
	s_waitcnt lgkmcnt(0)
	v_pk_add_f32 v[26:27], v[26:27], 1.0 op_sel_hi:[1,0]
	v_pk_add_f32 v[24:25], v[24:25], 1.0 op_sel_hi:[1,0]
	s_waitcnt lgkmcnt(0)
	v_pk_fma_f32 v[16:17], v[16:17], v[26:27], v[30:31]
	v_pk_fma_f32 v[14:15], v[14:15], v[24:25], v[28:29]
	s_nop 0
	v_cvt_pk_bf16_f32 v14, v14, v15
	v_cvt_pk_bf16_f32 v15, v16, v17
	global_store_dwordx2 v[20:21], v[14:15], off
.LBB0_278:
	ds_read_b128 v[24:27], v166 offset:16448
	ds_read_b128 v[28:31], v166 offset:17472
	v_mov_b32_e32 v14, v23
	v_mov_b32_e32 v15, v23
	v_sub_f32_e32 v11, v11, v22
	v_sub_f32_e32 v10, v10, v22
	v_sub_f32_e32 v13, v13, v22
	v_sub_f32_e32 v12, v12, v22
	v_mov_b32_e32 v16, v23
	v_mov_b32_e32 v17, v23
	v_pk_mul_f32 v[12:13], v[16:17], v[12:13]
	v_pk_mul_f32 v[10:11], v[14:15], v[10:11]
	s_and_b64 vcc, exec, s[42:43]
	v_readlane_b32 s8, v254, 54
	s_waitcnt lgkmcnt(0)
	v_pk_fma_f32 v[10:11], v[10:11], v[24:25], v[28:29]
	v_pk_fma_f32 v[12:13], v[12:13], v[26:27], v[30:31]
	v_cndmask_b32_e64 v11, v215, v11, s[40:41]
	v_cndmask_b32_e64 v13, v215, v13, s[40:41]
	v_cndmask_b32_e64 v12, v215, v12, s[40:41]
	v_cndmask_b32_e64 v10, v215, v10, s[40:41]
	global_store_dwordx4 v[18:19], v[10:13], off offset:64
	s_cbranch_vccnz .LBB0_280
	v_add_co_u32_e32 v24, vcc, 0x1000, v130
	s_nop 1
	v_addc_co_u32_e32 v25, vcc, 0, v131, vcc
	ds_read_b128 v[24:27], v166 offset:19520
	s_nop 0
	ds_read_b128 v[28:31], v166 offset:18496
	s_waitcnt lgkmcnt(0)
	v_pk_add_f32 v[26:27], v[26:27], 1.0 op_sel_hi:[1,0]
	v_pk_add_f32 v[24:25], v[24:25], 1.0 op_sel_hi:[1,0]
	s_waitcnt lgkmcnt(0)
	v_pk_fma_f32 v[12:13], v[12:13], v[26:27], v[30:31]
	v_pk_fma_f32 v[10:11], v[10:11], v[24:25], v[28:29]
	s_nop 0
	v_cvt_pk_bf16_f32 v10, v10, v11
	v_cvt_pk_bf16_f32 v11, v12, v13
	global_store_dwordx2 v[20:21], v[10:11], off offset:32
.LBB0_280:
	ds_read_b128 v[10:13], v166 offset:16896
	ds_read_b128 v[24:27], v166 offset:17920
	v_sub_f32_e32 v7, v7, v22
	v_sub_f32_e32 v6, v6, v22
	v_sub_f32_e32 v9, v9, v22
	v_sub_f32_e32 v8, v8, v22
	v_pk_mul_f32 v[8:9], v[16:17], v[8:9]
	v_pk_mul_f32 v[6:7], v[14:15], v[6:7]
	s_and_b64 vcc, exec, s[42:43]
	s_waitcnt lgkmcnt(0)
	v_pk_fma_f32 v[6:7], v[6:7], v[10:11], v[24:25]
	v_pk_fma_f32 v[8:9], v[8:9], v[12:13], v[26:27]
	v_cndmask_b32_e64 v7, v215, v7, s[40:41]
	v_cndmask_b32_e64 v9, v215, v9, s[40:41]
	v_cndmask_b32_e64 v8, v215, v8, s[40:41]
	v_cndmask_b32_e64 v6, v215, v6, s[40:41]
	global_store_dwordx4 v[18:19], v[6:9], off offset:512
	s_cbranch_vccnz .LBB0_282
	v_add_co_u32_e32 v10, vcc, 0x1000, v130
	s_nop 1
	v_addc_co_u32_e32 v11, vcc, 0, v131, vcc
	ds_read_b128 v[10:13], v166 offset:19968
	s_nop 0
	ds_read_b128 v[24:27], v166 offset:18944
	s_waitcnt lgkmcnt(0)
	v_pk_add_f32 v[12:13], v[12:13], 1.0 op_sel_hi:[1,0]
	v_pk_add_f32 v[10:11], v[10:11], 1.0 op_sel_hi:[1,0]
	s_waitcnt lgkmcnt(0)
	v_pk_fma_f32 v[8:9], v[8:9], v[12:13], v[26:27]
	v_pk_fma_f32 v[6:7], v[6:7], v[10:11], v[24:25]
	s_nop 0
	v_cvt_pk_bf16_f32 v6, v6, v7
	v_cvt_pk_bf16_f32 v7, v8, v9
	global_store_dwordx2 v[20:21], v[6:7], off offset:256
.LBB0_282:
	ds_read_b128 v[6:9], v166 offset:16960
	ds_read_b128 v[10:13], v166 offset:17984
	v_sub_f32_e32 v3, v3, v22
	v_sub_f32_e32 v2, v2, v22
	v_sub_f32_e32 v5, v5, v22
	v_sub_f32_e32 v4, v4, v22
	v_mov_b32_e32 v22, v23
	v_pk_mul_f32 v[4:5], v[22:23], v[4:5]
	v_pk_mul_f32 v[2:3], v[14:15], v[2:3]
	s_and_b64 vcc, exec, s[42:43]
	s_waitcnt lgkmcnt(0)
	v_pk_fma_f32 v[2:3], v[2:3], v[6:7], v[10:11]
	v_pk_fma_f32 v[4:5], v[4:5], v[8:9], v[12:13]
	v_cndmask_b32_e64 v3, v215, v3, s[40:41]
	v_cndmask_b32_e64 v5, v215, v5, s[40:41]
	v_cndmask_b32_e64 v4, v215, v4, s[40:41]
	v_cndmask_b32_e64 v2, v215, v2, s[40:41]
	global_store_dwordx4 v[18:19], v[2:5], off offset:576
	s_cbranch_vccnz .LBB0_284
	v_add_co_u32_e32 v6, vcc, 0x1000, v130
	s_nop 1
	v_addc_co_u32_e32 v7, vcc, 0, v131, vcc
	ds_read_b128 v[6:9], v166 offset:20032
	s_nop 0
	ds_read_b128 v[10:13], v166 offset:19008
	s_waitcnt lgkmcnt(0)
	v_pk_add_f32 v[8:9], v[8:9], 1.0 op_sel_hi:[1,0]
	v_pk_add_f32 v[6:7], v[6:7], 1.0 op_sel_hi:[1,0]
	s_waitcnt lgkmcnt(0)
	v_pk_fma_f32 v[4:5], v[4:5], v[8:9], v[12:13]
	v_pk_fma_f32 v[2:3], v[2:3], v[6:7], v[10:11]
	s_nop 0
	v_cvt_pk_bf16_f32 v2, v2, v3
	v_cvt_pk_bf16_f32 v3, v4, v5
	global_store_dwordx2 v[20:21], v[2:3], off offset:288

.LBB0_317:
	s_lshl_b32 s4, s56, 8
	s_cmpk_lt_u32 s4, 0x4000
	s_cselect_b32 s0, s90, 0x3000
	s_cmp_gt_i32 s56, 31
	v_lshl_or_b32 v122, s42, 8, v126
	s_cselect_b32 s0, s0, 0
	v_or_b32_e32 v154, s65, v122
	s_lshl_b32 s10, s0, 2
	s_add_u32 s0, s52, s10
	v_ashrrev_i32_e32 v155, 31, v154
	s_addc_u32 s1, s53, 0
	v_lshlrev_b64 v[156:157], 2, v[154:155]
	v_lshl_add_u64 v[122:123], s[0:1], 0, v[156:157]
	s_add_i32 s0, s4, s13
	v_or_b32_e32 v158, s0, v162
	v_ashrrev_i32_e32 v159, 31, v158
	v_lshlrev_b64 v[160:161], 12, v[158:159]
	s_barrier
	global_load_dwordx4 v[150:153], v[122:123], off
	global_load_dwordx4 v[146:149], v[122:123], off offset:64
	global_load_dwordx4 v[142:145], v[122:123], off offset:512
	global_load_dwordx4 v[138:141], v[122:123], off offset:576
	v_lshl_add_u64 v[122:123], s[54:55], 0, v[160:161]
	v_lshl_add_u64 v[164:165], v[122:123], 0, v[156:157]
	s_mov_b32 s0, 0x3fb504f3
	s_mov_b64 s[6:7], 0x10000
	s_mov_b64 s[8:9], 0x50000
	v_and_b32_e32 v0, 63, v163
	s_mov_b64 s[14:15], 0x10000
	s_mov_b64 s[16:17], 0x50000
	v_lshl_add_u64 v[244:245], v[164:165], 0, 0
	global_load_dwordx4 v[174:177], v[244:245], off
	global_load_dwordx4 v[178:181], v[244:245], off offset:64
	global_load_dwordx4 v[192:195], v[244:245], off offset:512
	global_load_dwordx4 v[196:199], v[244:245], off offset:576
	v_lshl_add_u64 v[244:245], v[244:245], 0, s[6:7]
	global_load_dwordx4 v[200:203], v[244:245], off
	global_load_dwordx4 v[204:207], v[244:245], off offset:64
	global_load_dwordx4 v[224:227], v[244:245], off offset:512
	global_load_dwordx4 v[228:231], v[244:245], off offset:576
	v_lshl_add_u64 v[244:245], v[244:245], 0, s[6:7]
	global_load_dwordx4 v[232:235], v[244:245], off
	global_load_dwordx4 v[236:239], v[244:245], off offset:64
	global_load_dwordx4 v[240:243], v[244:245], off offset:512
	global_load_dwordx4 v[168:171], v[244:245], off offset:576
	s_waitcnt vmcnt(11)
	v_pk_mul_f32 v[124:125], v[176:177], s[0:1] op_sel_hi:[1,0]
	v_pk_mul_f32 v[122:123], v[174:175], s[0:1] op_sel_hi:[1,0]
	v_lshl_add_u64 v[244:245], v[244:245], 0, s[6:7]
	global_load_dwordx4 v[174:177], v[244:245], off
	v_pk_fma_f32 v[128:129], v[120:121], v[152:153], v[124:125]
	v_pk_fma_f32 v[126:127], v[118:119], v[150:151], v[122:123]
	s_waitcnt vmcnt(11)
	v_pk_mul_f32 v[120:121], v[180:181], s[0:1] op_sel_hi:[1,0]
	v_pk_mul_f32 v[118:119], v[178:179], s[0:1] op_sel_hi:[1,0]
	global_load_dwordx4 v[178:181], v[244:245], off offset:64
	v_pk_fma_f32 v[124:125], v[116:117], v[148:149], v[120:121]
	v_pk_fma_f32 v[122:123], v[114:115], v[146:147], v[118:119]
	s_waitcnt vmcnt(11)
	v_pk_mul_f32 v[116:117], v[194:195], s[0:1] op_sel_hi:[1,0]
	v_pk_mul_f32 v[114:115], v[192:193], s[0:1] op_sel_hi:[1,0]
	global_load_dwordx4 v[192:195], v[244:245], off offset:512
	v_pk_fma_f32 v[112:113], v[112:113], v[144:145], v[116:117]
	v_pk_fma_f32 v[110:111], v[110:111], v[142:143], v[114:115]
	v_lshl_add_u64 v[164:165], v[164:165], 0, s[6:7]
	s_waitcnt vmcnt(11)
	v_pk_mul_f32 v[116:117], v[198:199], s[0:1] op_sel_hi:[1,0]
	v_pk_mul_f32 v[114:115], v[196:197], s[0:1] op_sel_hi:[1,0]
	global_load_dwordx4 v[196:199], v[244:245], off offset:576
	v_pk_fma_f32 v[100:101], v[100:101], v[140:141], v[116:117]
	v_pk_fma_f32 v[98:99], v[98:99], v[138:139], v[114:115]
	s_nop 0
	s_waitcnt vmcnt(11)
	v_pk_mul_f32 v[116:117], v[202:203], s[0:1] op_sel_hi:[1,0]
	v_pk_mul_f32 v[114:115], v[200:201], s[0:1] op_sel_hi:[1,0]
	v_lshl_add_u64 v[244:245], v[244:245], 0, s[8:9]
	global_load_dwordx4 v[200:203], v[244:245], off
	v_pk_fma_f32 v[120:121], v[108:109], v[152:153], v[116:117]
	v_pk_fma_f32 v[118:119], v[106:107], v[150:151], v[114:115]
	s_waitcnt vmcnt(11)
	v_pk_mul_f32 v[108:109], v[206:207], s[0:1] op_sel_hi:[1,0]
	v_pk_mul_f32 v[106:107], v[204:205], s[0:1] op_sel_hi:[1,0]
	global_load_dwordx4 v[204:207], v[244:245], off offset:64
	v_pk_fma_f32 v[116:117], v[104:105], v[148:149], v[108:109]
	v_pk_fma_f32 v[114:115], v[102:103], v[146:147], v[106:107]
	s_waitcnt vmcnt(11)
	v_pk_mul_f32 v[104:105], v[226:227], s[0:1] op_sel_hi:[1,0]
	v_pk_mul_f32 v[102:103], v[224:225], s[0:1] op_sel_hi:[1,0]
	global_load_dwordx4 v[224:227], v[244:245], off offset:512
	v_pk_fma_f32 v[104:105], v[96:97], v[144:145], v[104:105]
	v_pk_fma_f32 v[102:103], v[94:95], v[142:143], v[102:103]
	v_lshl_add_u64 v[164:165], v[164:165], 0, s[6:7]
	s_waitcnt vmcnt(11)
	v_pk_mul_f32 v[96:97], v[230:231], s[0:1] op_sel_hi:[1,0]
	v_pk_mul_f32 v[94:95], v[228:229], s[0:1] op_sel_hi:[1,0]
	global_load_dwordx4 v[228:231], v[244:245], off offset:576
	v_pk_fma_f32 v[88:89], v[88:89], v[140:141], v[96:97]
	v_pk_fma_f32 v[86:87], v[86:87], v[138:139], v[94:95]
	s_nop 0
	s_waitcnt vmcnt(11)
	v_pk_mul_f32 v[96:97], v[234:235], s[0:1] op_sel_hi:[1,0]
	v_pk_mul_f32 v[94:95], v[232:233], s[0:1] op_sel_hi:[1,0]
	v_lshl_add_u64 v[244:245], v[244:245], 0, s[6:7]
	global_load_dwordx4 v[232:235], v[244:245], off
	v_pk_fma_f32 v[108:109], v[92:93], v[152:153], v[96:97]
	v_pk_fma_f32 v[106:107], v[90:91], v[150:151], v[94:95]
	s_waitcnt vmcnt(11)
	v_pk_mul_f32 v[92:93], v[238:239], s[0:1] op_sel_hi:[1,0]
	v_pk_mul_f32 v[90:91], v[236:237], s[0:1] op_sel_hi:[1,0]
	global_load_dwordx4 v[236:239], v[244:245], off offset:64
	v_pk_fma_f32 v[96:97], v[84:85], v[148:149], v[92:93]
	v_pk_fma_f32 v[94:95], v[82:83], v[146:147], v[90:91]
	s_waitcnt vmcnt(11)
	v_pk_mul_f32 v[84:85], v[242:243], s[0:1] op_sel_hi:[1,0]
	v_pk_mul_f32 v[82:83], v[240:241], s[0:1] op_sel_hi:[1,0]
	global_load_dwordx4 v[240:243], v[244:245], off offset:512
	v_pk_fma_f32 v[84:85], v[80:81], v[144:145], v[84:85]
	v_pk_fma_f32 v[82:83], v[78:79], v[142:143], v[82:83]
	v_lshl_add_u64 v[164:165], v[164:165], 0, s[6:7]
	s_waitcnt vmcnt(11)
	v_pk_mul_f32 v[80:81], v[170:171], s[0:1] op_sel_hi:[1,0]
	v_pk_mul_f32 v[78:79], v[168:169], s[0:1] op_sel_hi:[1,0]
	global_load_dwordx4 v[168:171], v[244:245], off offset:576
	v_pk_fma_f32 v[72:73], v[72:73], v[140:141], v[80:81]
	v_pk_fma_f32 v[70:71], v[70:71], v[138:139], v[78:79]
	s_nop 0
	s_waitcnt vmcnt(11)
	v_pk_mul_f32 v[80:81], v[176:177], s[0:1] op_sel_hi:[1,0]
	v_pk_mul_f32 v[78:79], v[174:175], s[0:1] op_sel_hi:[1,0]
	v_lshl_add_u64 v[244:245], v[244:245], 0, s[6:7]
	global_load_dwordx4 v[174:177], v[244:245], off
	v_pk_fma_f32 v[92:93], v[76:77], v[152:153], v[80:81]
	v_pk_fma_f32 v[90:91], v[74:75], v[150:151], v[78:79]
	s_waitcnt vmcnt(11)
	v_pk_mul_f32 v[76:77], v[180:181], s[0:1] op_sel_hi:[1,0]
	v_pk_mul_f32 v[74:75], v[178:179], s[0:1] op_sel_hi:[1,0]
	global_load_dwordx4 v[178:181], v[244:245], off offset:64
	v_pk_fma_f32 v[80:81], v[68:69], v[148:149], v[76:77]
	v_pk_fma_f32 v[78:79], v[66:67], v[146:147], v[74:75]
	s_waitcnt vmcnt(11)
	v_pk_mul_f32 v[68:69], v[194:195], s[0:1] op_sel_hi:[1,0]
	v_pk_mul_f32 v[66:67], v[192:193], s[0:1] op_sel_hi:[1,0]
	global_load_dwordx4 v[192:195], v[244:245], off offset:512
	v_pk_fma_f32 v[68:69], v[64:65], v[144:145], v[68:69]
	v_pk_fma_f32 v[66:67], v[62:63], v[142:143], v[66:67]
	v_lshl_add_u64 v[164:165], v[164:165], 0, s[8:9]
	s_waitcnt vmcnt(11)
	v_pk_mul_f32 v[64:65], v[198:199], s[0:1] op_sel_hi:[1,0]
	v_pk_mul_f32 v[62:63], v[196:197], s[0:1] op_sel_hi:[1,0]
	global_load_dwordx4 v[196:199], v[244:245], off offset:576
	v_pk_fma_f32 v[56:57], v[56:57], v[140:141], v[64:65]
	v_pk_fma_f32 v[54:55], v[54:55], v[138:139], v[62:63]
	s_nop 0
	s_waitcnt vmcnt(11)
	v_pk_mul_f32 v[64:65], v[202:203], s[0:1] op_sel_hi:[1,0]
	v_pk_mul_f32 v[62:63], v[200:201], s[0:1] op_sel_hi:[1,0]
	v_lshl_add_u64 v[244:245], v[244:245], 0, s[6:7]
	global_load_dwordx4 v[200:203], v[244:245], off
	v_pk_fma_f32 v[76:77], v[60:61], v[152:153], v[64:65]
	v_pk_fma_f32 v[74:75], v[58:59], v[150:151], v[62:63]
	s_waitcnt vmcnt(11)
	v_pk_mul_f32 v[60:61], v[206:207], s[0:1] op_sel_hi:[1,0]
	v_pk_mul_f32 v[58:59], v[204:205], s[0:1] op_sel_hi:[1,0]
	global_load_dwordx4 v[204:207], v[244:245], off offset:64
	v_pk_fma_f32 v[64:65], v[52:53], v[148:149], v[60:61]
	v_pk_fma_f32 v[62:63], v[50:51], v[146:147], v[58:59]
	s_waitcnt vmcnt(11)
	v_pk_mul_f32 v[52:53], v[226:227], s[0:1] op_sel_hi:[1,0]
	v_pk_mul_f32 v[50:51], v[224:225], s[0:1] op_sel_hi:[1,0]
	global_load_dwordx4 v[224:227], v[244:245], off offset:512
	v_pk_fma_f32 v[52:53], v[48:49], v[144:145], v[52:53]
	v_pk_fma_f32 v[50:51], v[46:47], v[142:143], v[50:51]
	v_lshl_add_u64 v[164:165], v[164:165], 0, s[6:7]
	s_waitcnt vmcnt(11)
	v_pk_mul_f32 v[48:49], v[230:231], s[0:1] op_sel_hi:[1,0]
	v_pk_mul_f32 v[46:47], v[228:229], s[0:1] op_sel_hi:[1,0]
	global_load_dwordx4 v[228:231], v[244:245], off offset:576
	v_pk_fma_f32 v[40:41], v[40:41], v[140:141], v[48:49]
	v_pk_fma_f32 v[38:39], v[38:39], v[138:139], v[46:47]
	s_nop 0
	s_waitcnt vmcnt(11)
	v_pk_mul_f32 v[48:49], v[234:235], s[0:1] op_sel_hi:[1,0]
	v_pk_mul_f32 v[46:47], v[232:233], s[0:1] op_sel_hi:[1,0]
	v_pk_fma_f32 v[60:61], v[44:45], v[152:153], v[48:49]
	v_pk_fma_f32 v[58:59], v[42:43], v[150:151], v[46:47]
	s_waitcnt vmcnt(10)
	v_pk_mul_f32 v[44:45], v[238:239], s[0:1] op_sel_hi:[1,0]
	v_pk_mul_f32 v[42:43], v[236:237], s[0:1] op_sel_hi:[1,0]
	v_pk_fma_f32 v[48:49], v[36:37], v[148:149], v[44:45]
	v_pk_fma_f32 v[46:47], v[34:35], v[146:147], v[42:43]
	s_waitcnt vmcnt(9)
	v_pk_mul_f32 v[36:37], v[242:243], s[0:1] op_sel_hi:[1,0]
	v_pk_mul_f32 v[34:35], v[240:241], s[0:1] op_sel_hi:[1,0]
	v_pk_fma_f32 v[36:37], v[32:33], v[144:145], v[36:37]
	v_pk_fma_f32 v[34:35], v[30:31], v[142:143], v[34:35]
	v_lshl_add_u64 v[164:165], v[164:165], 0, s[6:7]
	s_waitcnt vmcnt(8)
	v_pk_mul_f32 v[32:33], v[170:171], s[0:1] op_sel_hi:[1,0]
	v_pk_mul_f32 v[30:31], v[168:169], s[0:1] op_sel_hi:[1,0]
	v_pk_fma_f32 v[28:29], v[28:29], v[140:141], v[32:33]
	v_pk_fma_f32 v[26:27], v[26:27], v[138:139], v[30:31]
	s_nop 0
	s_waitcnt vmcnt(7)
	v_pk_mul_f32 v[32:33], v[176:177], s[0:1] op_sel_hi:[1,0]
	v_pk_mul_f32 v[30:31], v[174:175], s[0:1] op_sel_hi:[1,0]
	v_pk_fma_f32 v[44:45], v[24:25], v[152:153], v[32:33]
	v_pk_fma_f32 v[42:43], v[22:23], v[150:151], v[30:31]
	s_waitcnt vmcnt(6)
	v_pk_mul_f32 v[24:25], v[180:181], s[0:1] op_sel_hi:[1,0]
	v_pk_mul_f32 v[22:23], v[178:179], s[0:1] op_sel_hi:[1,0]
	v_pk_fma_f32 v[32:33], v[20:21], v[148:149], v[24:25]
	v_pk_fma_f32 v[30:31], v[18:19], v[146:147], v[22:23]
	s_waitcnt vmcnt(5)
	v_pk_mul_f32 v[20:21], v[194:195], s[0:1] op_sel_hi:[1,0]
	v_pk_mul_f32 v[18:19], v[192:193], s[0:1] op_sel_hi:[1,0]
	v_pk_fma_f32 v[24:25], v[16:17], v[144:145], v[20:21]
	v_pk_fma_f32 v[22:23], v[14:15], v[142:143], v[18:19]
	v_lshl_add_u64 v[164:165], v[164:165], 0, s[6:7]
	s_waitcnt vmcnt(4)
	v_pk_mul_f32 v[16:17], v[198:199], s[0:1] op_sel_hi:[1,0]
	v_pk_mul_f32 v[14:15], v[196:197], s[0:1] op_sel_hi:[1,0]
	v_pk_fma_f32 v[20:21], v[12:13], v[140:141], v[16:17]
	v_pk_fma_f32 v[18:19], v[10:11], v[138:139], v[14:15]
	s_nop 0
	s_waitcnt vmcnt(3)
	v_pk_mul_f32 v[12:13], v[202:203], s[0:1] op_sel_hi:[1,0]
	v_pk_mul_f32 v[10:11], v[200:201], s[0:1] op_sel_hi:[1,0]
	v_pk_fma_f32 v[16:17], v[136:137], v[152:153], v[12:13]
	v_pk_fma_f32 v[14:15], v[134:135], v[150:151], v[10:11]
	v_mov_b32_e32 v134, v126
	v_mov_b32_e32 v135, v129
	v_mov_b32_e32 v136, v122
	v_mov_b32_e32 v137, v125
	s_waitcnt vmcnt(2)
	v_pk_mul_f32 v[12:13], v[206:207], s[0:1] op_sel_hi:[1,0]
	v_pk_mul_f32 v[10:11], v[204:205], s[0:1] op_sel_hi:[1,0]
	v_pk_fma_f32 v[12:13], v[132:133], v[148:149], v[12:13]
	v_pk_fma_f32 v[10:11], v[130:131], v[146:147], v[10:11]
	s_waitcnt vmcnt(1)
	v_pk_mul_f32 v[132:133], v[226:227], s[0:1] op_sel_hi:[1,0]
	v_pk_mul_f32 v[130:131], v[224:225], s[0:1] op_sel_hi:[1,0]
	v_pk_fma_f32 v[8:9], v[8:9], v[144:145], v[132:133]
	v_pk_fma_f32 v[6:7], v[6:7], v[142:143], v[130:131]
	s_waitcnt vmcnt(0)
	v_pk_mul_f32 v[132:133], v[230:231], s[0:1] op_sel_hi:[1,0]
	v_pk_mul_f32 v[130:131], v[228:229], s[0:1] op_sel_hi:[1,0]
	v_pk_fma_f32 v[4:5], v[4:5], v[140:141], v[132:133]
	v_pk_fma_f32 v[2:3], v[2:3], v[138:139], v[130:131]
	v_lshl_add_u64 v[130:131], v[164:165], 0, s[8:9]
	v_xor_b32_e32 v132, 32, v214
	v_and_b32_e32 v131, 64, v214
	v_xor_b32_e32 v130, 16, v214
	v_add_u32_e32 v131, 64, v131
	v_cmp_lt_i32_e32 vcc, v130, v131
	v_mov_b32_e32 v133, v128
	v_add_f32_e32 v139, v112, v113
	v_cndmask_b32_e32 v130, v214, v130, vcc
	v_cmp_lt_i32_e32 vcc, v132, v131
	v_mov_b32_e32 v138, v99
	v_lshlrev_b32_e32 v130, 2, v130
	v_cndmask_b32_e32 v131, v214, v132, vcc
	v_mov_b32_e32 v132, v127
	v_pk_add_f32 v[132:133], v[132:133], v[134:135]
	v_mov_b32_e32 v134, v123
	v_mov_b32_e32 v135, v124
	v_pk_add_f32 v[134:135], v[134:135], v[136:137]
	v_add_f32_e32 v132, v132, v133
	v_pk_add_f32 v[134:135], v[134:135], v[134:135] op_sel_hi:[0,1]
	v_add_f32_e32 v133, 0, v132
	v_add_f32_e32 v137, v110, v111
	v_mov_b32_e32 v136, v98
	v_mov_b32_e32 v134, v100
	v_mov_b32_e32 v132, v101
	v_pk_add_f32 v[136:137], v[136:137], v[138:139]
	v_pk_add_f32 v[132:133], v[134:135], v[132:133]
	v_lshlrev_b32_e32 v131, 2, v131
	v_pk_add_f32 v[132:133], v[136:137], v[132:133]
	s_lshl_b32 s0, s41, 3
	v_add_f32_e32 v132, v132, v133
	ds_bpermute_b32 v133, v130, v132
	v_cmp_gt_u32_e32 vcc, 16, v0
	s_add_i32 s5, s0, 0
	s_waitcnt lgkmcnt(0)
	v_add_f32_e32 v132, v132, v133
	ds_bpermute_b32 v133, v131, v132
	s_waitcnt lgkmcnt(0)
	v_add_f32_e32 v132, v132, v133
	v_fmamk_f32 v134, v132, 0xbc800000, v129
	v_fmamk_f32 v136, v132, 0xbc800000, v127
	v_fmamk_f32 v133, v132, 0xbc800000, v128
	v_fmamk_f32 v135, v132, 0xbc800000, v126
	v_mul_f32_e32 v136, v136, v136
	v_mul_f32_e32 v134, v134, v134
	v_fmac_f32_e32 v136, v135, v135
	v_fmac_f32_e32 v134, v133, v133
	v_fmamk_f32 v135, v132, 0xbc800000, v125
	v_fmamk_f32 v137, v132, 0xbc800000, v123
	v_add_f32_e32 v133, v136, v134
	v_fmamk_f32 v134, v132, 0xbc800000, v124
	v_fmamk_f32 v136, v132, 0xbc800000, v122
	v_mul_f32_e32 v137, v137, v137
	v_mul_f32_e32 v135, v135, v135
	v_fmac_f32_e32 v137, v136, v136
	v_fmac_f32_e32 v135, v134, v134
	v_add_f32_e32 v134, v137, v135
	v_fmamk_f32 v135, v132, 0xbc800000, v113
	v_fmamk_f32 v137, v132, 0xbc800000, v111
	v_add_f32_e32 v133, v133, v134
	v_fmamk_f32 v134, v132, 0xbc800000, v112
	v_fmamk_f32 v136, v132, 0xbc800000, v110
	v_mul_f32_e32 v137, v137, v137
	v_mul_f32_e32 v135, v135, v135
	v_fmac_f32_e32 v137, v136, v136
	v_fmac_f32_e32 v135, v134, v134
	v_add_f32_e32 v134, v137, v135
	v_fmamk_f32 v135, v132, 0xbc800000, v101
	v_fmamk_f32 v137, v132, 0xbc800000, v99
	v_add_f32_e32 v133, v134, v133
	v_fmamk_f32 v134, v132, 0xbc800000, v100
	v_fmamk_f32 v136, v132, 0xbc800000, v98
	v_mul_f32_e32 v137, v137, v137
	v_mul_f32_e32 v135, v135, v135
	v_fmac_f32_e32 v137, v136, v136
	v_fmac_f32_e32 v135, v134, v134
	v_add_f32_e32 v134, v137, v135
	v_add_f32_e32 v133, v134, v133
	ds_bpermute_b32 v134, v130, v133
	s_waitcnt lgkmcnt(0)
	v_add_f32_e32 v133, v133, v134
	ds_bpermute_b32 v134, v131, v133
	s_and_saveexec_b64 s[0:1], vcc
	s_mov_b32 s72, 0xa000
	s_mov_b32 s35, s89
	v_readlane_b32 s8, v253, 49
	s_cbranch_execz .LBB0_319
	s_lshl_b32 s6, s40, 11
	s_add_i32 s6, s5, s6
	v_mul_f32_e32 v132, 0x3c800000, v132
	v_lshl_add_u32 v135, v162, 5, s6
	s_waitcnt lgkmcnt(0)
	v_add_f32_e32 v133, v133, v134
	ds_write_b64 v135, v[132:133]

.Lfln_fill_done_b:
	v_and_b32_e32 v166, 0x3ff, v156
	s_waitcnt lgkmcnt(0)
	s_barrier
	v_lshl_add_u64 v[130:131], s[48:49], 0, v[156:157]
	v_lshl_add_u64 v[132:133], s[50:51], 0, v[156:157]
	ds_read_b128 v[144:147], v166 offset:16384
	ds_read_b128 v[148:151], v166 offset:17408
	v_readlane_b32 s0, v254, 8
	v_readlane_b32 s1, v254, 9
	v_readlane_b32 s2, v254, 10
	v_lshlrev_b64 v[136:137], 11, v[158:159]
	v_lshl_add_u64 v[134:135], s[0:1], 0, v[160:161]
	s_add_u32 s0, s46, s10
	v_lshl_add_u64 v[138:139], v[134:135], 0, v[156:157]
	v_lshl_add_u64 v[134:135], s[18:19], 0, v[136:137]
	s_addc_u32 s1, s47, 0
	s_lshl_b32 s2, s13, 3
	v_lshl_add_u64 v[140:141], v[154:155], 1, v[134:135]
	v_lshl_add_u64 v[134:135], s[0:1], 0, v[156:157]
	s_add_i32 s0, s2, 0
	s_waitcnt lgkmcnt(0)
	v_cmp_eq_u32_e64 s[40:41], 0, v0
	v_lshl_add_u32 v0, v162, 3, s0
	ds_read_b64 v[142:143], v0 offset:8192
	s_cmp_lg_u64 s[46:47], 0
	s_mov_b64 s[0:1], 0x1000
	v_lshl_add_u64 v[136:137], v[134:135], 0, s[0:1]
	s_cselect_b64 s[0:1], -1, 0
	s_waitcnt lgkmcnt(0)
	v_sub_f32_e32 v129, v129, v142
	v_sub_f32_e32 v128, v128, v142
	v_sub_f32_e32 v127, v127, v142
	v_sub_f32_e32 v126, v126, v142
	v_pk_mul_f32 v[126:127], v[142:143], v[126:127] op_sel:[1,0]
	v_pk_mul_f32 v[128:129], v[142:143], v[128:129] op_sel:[1,0]
	s_cmp_eq_u64 s[46:47], 0
	v_readlane_b32 s3, v254, 11
	s_waitcnt lgkmcnt(0)
	v_pk_fma_f32 v[128:129], v[146:147], v[128:129], v[150:151]
	v_pk_fma_f32 v[126:127], v[144:145], v[126:127], v[148:149]
	v_cndmask_b32_e64 v129, v215, v129, s[40:41]
	v_cndmask_b32_e64 v128, v215, v128, s[40:41]
	v_cndmask_b32_e64 v127, v215, v127, s[40:41]
	v_cndmask_b32_e64 v126, v215, v126, s[40:41]
	global_store_dwordx4 v[138:139], v[126:129], off
	s_cbranch_scc1 .LBB0_359
	ds_read_b128 v[144:147], v166 offset:19456
	ds_read_b128 v[148:151], v166 offset:18432
	s_waitcnt lgkmcnt(0)
	v_pk_add_f32 v[146:147], v[146:147], 1.0 op_sel_hi:[1,0]
	v_pk_add_f32 v[144:145], v[144:145], 1.0 op_sel_hi:[1,0]
	s_waitcnt lgkmcnt(0)
	v_pk_fma_f32 v[128:129], v[128:129], v[146:147], v[150:151]
	v_pk_fma_f32 v[126:127], v[126:127], v[144:145], v[148:149]
	s_nop 0
	v_cvt_pk_bf16_f32 v126, v126, v127
	v_cvt_pk_bf16_f32 v127, v128, v129
	global_store_dwordx2 v[140:141], v[126:127], off
.LBB0_359:
	ds_read_b128 v[144:147], v166 offset:16448
	ds_read_b128 v[148:151], v166 offset:17472
	v_mov_b32_e32 v126, v143
	v_mov_b32_e32 v127, v143
	v_sub_f32_e32 v123, v123, v142
	v_sub_f32_e32 v122, v122, v142
	v_sub_f32_e32 v125, v125, v142
	v_sub_f32_e32 v124, v124, v142
	v_mov_b32_e32 v128, v143
	v_mov_b32_e32 v129, v143
	v_pk_mul_f32 v[124:125], v[128:129], v[124:125]
	v_pk_mul_f32 v[122:123], v[126:127], v[122:123]
	s_andn2_b64 vcc, exec, s[0:1]
	s_waitcnt lgkmcnt(0)
	v_pk_fma_f32 v[122:123], v[122:123], v[144:145], v[148:149]
	v_pk_fma_f32 v[124:125], v[124:125], v[146:147], v[150:151]
	v_cndmask_b32_e64 v144, 0, 1, s[0:1]
	v_cndmask_b32_e64 v125, v215, v125, s[40:41]
	v_cndmask_b32_e64 v124, v215, v124, s[40:41]
	v_cndmask_b32_e64 v123, v215, v123, s[40:41]
	v_cndmask_b32_e64 v122, v215, v122, s[40:41]
	v_cmp_ne_u32_e64 s[42:43], 1, v144
	global_store_dwordx4 v[138:139], v[122:125], off offset:64
	s_cbranch_vccnz .LBB0_361
	v_add_co_u32_e32 v144, vcc, 0x1000, v134
	s_nop 1
	v_addc_co_u32_e32 v145, vcc, 0, v135, vcc
	ds_read_b128 v[144:147], v166 offset:19520
	s_nop 0
	ds_read_b128 v[148:151], v166 offset:18496
	s_waitcnt lgkmcnt(0)
	v_pk_add_f32 v[146:147], v[146:147], 1.0 op_sel_hi:[1,0]
	v_pk_add_f32 v[144:145], v[144:145], 1.0 op_sel_hi:[1,0]
	s_waitcnt lgkmcnt(0)
	v_pk_fma_f32 v[124:125], v[124:125], v[146:147], v[150:151]
	v_pk_fma_f32 v[122:123], v[122:123], v[144:145], v[148:149]
	s_nop 0
	v_cvt_pk_bf16_f32 v122, v122, v123
	v_cvt_pk_bf16_f32 v123, v124, v125
	global_store_dwordx2 v[140:141], v[122:123], off offset:32
.LBB0_361:
	ds_read_b128 v[122:125], v166 offset:16896
	ds_read_b128 v[144:147], v166 offset:17920
	v_sub_f32_e32 v111, v111, v142
	v_sub_f32_e32 v110, v110, v142
	v_sub_f32_e32 v113, v113, v142
	v_sub_f32_e32 v112, v112, v142
	v_pk_mul_f32 v[112:113], v[128:129], v[112:113]
	v_pk_mul_f32 v[110:111], v[126:127], v[110:111]
	s_and_b64 vcc, exec, s[42:43]
	s_waitcnt lgkmcnt(0)
	v_pk_fma_f32 v[110:111], v[110:111], v[122:123], v[144:145]
	v_pk_fma_f32 v[112:113], v[112:113], v[124:125], v[146:147]
	v_cndmask_b32_e64 v111, v215, v111, s[40:41]
	v_cndmask_b32_e64 v113, v215, v113, s[40:41]
	v_cndmask_b32_e64 v112, v215, v112, s[40:41]
	v_cndmask_b32_e64 v110, v215, v110, s[40:41]
	global_store_dwordx4 v[138:139], v[110:113], off offset:512
	s_cbranch_vccnz .LBB0_363
	v_add_co_u32_e32 v122, vcc, 0x1000, v134
	s_nop 1
	v_addc_co_u32_e32 v123, vcc, 0, v135, vcc
	ds_read_b128 v[122:125], v166 offset:19968
	s_nop 0
	ds_read_b128 v[144:147], v166 offset:18944
	s_waitcnt lgkmcnt(0)
	v_pk_add_f32 v[124:125], v[124:125], 1.0 op_sel_hi:[1,0]
	v_pk_add_f32 v[122:123], v[122:123], 1.0 op_sel_hi:[1,0]
	s_waitcnt lgkmcnt(0)
	v_pk_fma_f32 v[112:113], v[112:113], v[124:125], v[146:147]
	v_pk_fma_f32 v[110:111], v[110:111], v[122:123], v[144:145]
	s_nop 0
	v_cvt_pk_bf16_f32 v110, v110, v111
	v_cvt_pk_bf16_f32 v111, v112, v113
	global_store_dwordx2 v[140:141], v[110:111], off offset:256
.LBB0_363:
	ds_read_b128 v[110:113], v166 offset:16960
	ds_read_b128 v[122:125], v166 offset:17984
	v_sub_f32_e32 v99, v99, v142
	v_sub_f32_e32 v98, v98, v142
	v_sub_f32_e32 v101, v101, v142
	v_sub_f32_e32 v100, v100, v142
	v_mov_b32_e32 v142, v143
	v_pk_mul_f32 v[100:101], v[142:143], v[100:101]
	v_pk_mul_f32 v[98:99], v[126:127], v[98:99]
	s_and_b64 vcc, exec, s[42:43]
	s_waitcnt lgkmcnt(0)
	v_pk_fma_f32 v[98:99], v[98:99], v[110:111], v[122:123]
	v_pk_fma_f32 v[100:101], v[100:101], v[112:113], v[124:125]
	v_cndmask_b32_e64 v99, v215, v99, s[40:41]
	v_cndmask_b32_e64 v101, v215, v101, s[40:41]
	v_cndmask_b32_e64 v100, v215, v100, s[40:41]
	v_cndmask_b32_e64 v98, v215, v98, s[40:41]
	global_store_dwordx4 v[138:139], v[98:101], off offset:576
	s_cbranch_vccnz .LBB0_365
	v_add_co_u32_e32 v110, vcc, 0x1000, v134
	s_nop 1
	v_addc_co_u32_e32 v111, vcc, 0, v135, vcc
	ds_read_b128 v[110:113], v166 offset:20032
	s_nop 0
	ds_read_b128 v[122:125], v166 offset:19008
	s_waitcnt lgkmcnt(0)
	v_pk_add_f32 v[112:113], v[112:113], 1.0 op_sel_hi:[1,0]
	v_pk_add_f32 v[110:111], v[110:111], 1.0 op_sel_hi:[1,0]
	s_waitcnt lgkmcnt(0)
	v_pk_fma_f32 v[100:101], v[100:101], v[112:113], v[124:125]
	v_pk_fma_f32 v[98:99], v[98:99], v[110:111], v[122:123]
	s_nop 0
	v_cvt_pk_bf16_f32 v98, v98, v99
	v_cvt_pk_bf16_f32 v99, v100, v101
	global_store_dwordx2 v[140:141], v[98:99], off offset:288

.LBB0_367:
	ds_read_b128 v[98:101], v166 offset:16448
	ds_read_b128 v[124:127], v166 offset:17472
	v_mov_b32_e32 v118, v123
	v_mov_b32_e32 v119, v123
	v_sub_f32_e32 v121, v115, v122
	v_sub_f32_e32 v120, v114, v122
	v_sub_f32_e32 v117, v117, v122
	v_sub_f32_e32 v116, v116, v122
	v_mov_b32_e32 v114, v123
	v_mov_b32_e32 v115, v123
	v_pk_mul_f32 v[116:117], v[114:115], v[116:117]
	v_pk_mul_f32 v[120:121], v[118:119], v[120:121]
	s_and_b64 vcc, exec, s[42:43]
	s_waitcnt lgkmcnt(0)
	v_pk_fma_f32 v[98:99], v[120:121], v[98:99], v[124:125]
	v_pk_fma_f32 v[100:101], v[116:117], v[100:101], v[126:127]
	v_cndmask_b32_e64 v99, v215, v99, s[40:41]
	v_cndmask_b32_e64 v101, v215, v101, s[40:41]
	v_cndmask_b32_e64 v100, v215, v100, s[40:41]
	v_cndmask_b32_e64 v98, v215, v98, s[40:41]
	global_store_dwordx4 v[110:111], v[98:101], off offset:64
	s_cbranch_vccnz .LBB0_369
	v_add_co_u32_e32 v116, vcc, 0x1000, v134
	s_nop 1
	v_addc_co_u32_e32 v117, vcc, 0, v135, vcc
	ds_read_b128 v[124:127], v166 offset:19520
	ds_read_b128 v[138:141], v166 offset:18496
	s_waitcnt lgkmcnt(0)
	v_pk_add_f32 v[116:117], v[126:127], 1.0 op_sel_hi:[1,0]
	v_pk_add_f32 v[120:121], v[124:125], 1.0 op_sel_hi:[1,0]
	s_waitcnt lgkmcnt(0)
	v_pk_fma_f32 v[100:101], v[100:101], v[116:117], v[140:141]
	v_pk_fma_f32 v[98:99], v[98:99], v[120:121], v[138:139]
	s_nop 0
	v_cvt_pk_bf16_f32 v98, v98, v99
	v_cvt_pk_bf16_f32 v99, v100, v101
	global_store_dwordx2 v[112:113], v[98:99], off offset:32
.LBB0_369:
	ds_read_b128 v[98:101], v166 offset:16896
	ds_read_b128 v[124:127], v166 offset:17920
	v_sub_f32_e32 v103, v103, v122
	v_sub_f32_e32 v102, v102, v122
	v_sub_f32_e32 v105, v105, v122
	v_sub_f32_e32 v104, v104, v122
	v_pk_mul_f32 v[104:105], v[114:115], v[104:105]
	v_pk_mul_f32 v[102:103], v[118:119], v[102:103]
	s_and_b64 vcc, exec, s[42:43]
	s_waitcnt lgkmcnt(0)
	v_pk_fma_f32 v[98:99], v[102:103], v[98:99], v[124:125]
	v_pk_fma_f32 v[100:101], v[104:105], v[100:101], v[126:127]
	v_cndmask_b32_e64 v99, v215, v99, s[40:41]
	v_cndmask_b32_e64 v101, v215, v101, s[40:41]
	v_cndmask_b32_e64 v100, v215, v100, s[40:41]
	v_cndmask_b32_e64 v98, v215, v98, s[40:41]
	global_store_dwordx4 v[110:111], v[98:101], off offset:512
	s_cbranch_vccnz .LBB0_371
	v_add_co_u32_e32 v102, vcc, 0x1000, v134
	s_nop 1
	v_addc_co_u32_e32 v103, vcc, 0, v135, vcc
	ds_read_b128 v[102:105], v166 offset:19968
	s_nop 0
	ds_read_b128 v[114:117], v166 offset:18944
	s_waitcnt lgkmcnt(0)
	v_pk_add_f32 v[104:105], v[104:105], 1.0 op_sel_hi:[1,0]
	v_pk_add_f32 v[102:103], v[102:103], 1.0 op_sel_hi:[1,0]
	s_waitcnt lgkmcnt(0)
	v_pk_fma_f32 v[100:101], v[100:101], v[104:105], v[116:117]
	v_pk_fma_f32 v[98:99], v[98:99], v[102:103], v[114:115]
	s_nop 0
	v_cvt_pk_bf16_f32 v98, v98, v99
	v_cvt_pk_bf16_f32 v99, v100, v101
	global_store_dwordx2 v[112:113], v[98:99], off offset:256
.LBB0_371:
	ds_read_b128 v[98:101], v166 offset:16960
	ds_read_b128 v[102:105], v166 offset:17984
	v_sub_f32_e32 v87, v87, v122
	v_sub_f32_e32 v86, v86, v122
	v_sub_f32_e32 v89, v89, v122
	v_sub_f32_e32 v88, v88, v122
	v_mov_b32_e32 v122, v123
	v_pk_mul_f32 v[88:89], v[122:123], v[88:89]
	v_pk_mul_f32 v[86:87], v[118:119], v[86:87]
	s_and_b64 vcc, exec, s[42:43]
	s_waitcnt lgkmcnt(0)
	v_pk_fma_f32 v[86:87], v[86:87], v[98:99], v[102:103]
	v_pk_fma_f32 v[88:89], v[88:89], v[100:101], v[104:105]
	v_cndmask_b32_e64 v87, v215, v87, s[40:41]
	v_cndmask_b32_e64 v89, v215, v89, s[40:41]
	v_cndmask_b32_e64 v88, v215, v88, s[40:41]
	v_cndmask_b32_e64 v86, v215, v86, s[40:41]
	global_store_dwordx4 v[110:111], v[86:89], off offset:576
	s_cbranch_vccnz .LBB0_373
	v_add_co_u32_e32 v98, vcc, 0x1000, v134
	s_nop 1
	v_addc_co_u32_e32 v99, vcc, 0, v135, vcc
	ds_read_b128 v[98:101], v166 offset:20032
	s_nop 0
	ds_read_b128 v[102:105], v166 offset:19008
	s_waitcnt lgkmcnt(0)
	v_pk_add_f32 v[100:101], v[100:101], 1.0 op_sel_hi:[1,0]
	v_pk_add_f32 v[98:99], v[98:99], 1.0 op_sel_hi:[1,0]
	s_waitcnt lgkmcnt(0)
	v_pk_fma_f32 v[88:89], v[88:89], v[100:101], v[104:105]
	v_pk_fma_f32 v[86:87], v[86:87], v[98:99], v[102:103]
	s_nop 0
	v_cvt_pk_bf16_f32 v86, v86, v87
	v_cvt_pk_bf16_f32 v87, v88, v89
	global_store_dwordx2 v[112:113], v[86:87], off offset:288

.LBB0_375:
	ds_read_b128 v[86:89], v166 offset:16448
	ds_read_b128 v[106:109], v166 offset:17472
	v_mov_b32_e32 v104, v103
	v_mov_b32_e32 v105, v103
	v_sub_f32_e32 v111, v95, v102
	v_sub_f32_e32 v110, v94, v102
	v_sub_f32_e32 v97, v97, v102
	v_sub_f32_e32 v96, v96, v102
	v_mov_b32_e32 v94, v103
	v_mov_b32_e32 v95, v103
	v_pk_mul_f32 v[96:97], v[94:95], v[96:97]
	v_pk_mul_f32 v[110:111], v[104:105], v[110:111]
	s_and_b64 vcc, exec, s[42:43]
	s_waitcnt lgkmcnt(0)
	v_pk_fma_f32 v[86:87], v[110:111], v[86:87], v[106:107]
	v_pk_fma_f32 v[88:89], v[96:97], v[88:89], v[108:109]
	v_cndmask_b32_e64 v87, v215, v87, s[40:41]
	v_cndmask_b32_e64 v89, v215, v89, s[40:41]
	v_cndmask_b32_e64 v88, v215, v88, s[40:41]
	v_cndmask_b32_e64 v86, v215, v86, s[40:41]
	global_store_dwordx4 v[98:99], v[86:89], off offset:64
	s_cbranch_vccnz .LBB0_377
	v_add_co_u32_e32 v96, vcc, 0x1000, v134
	s_nop 1
	v_addc_co_u32_e32 v97, vcc, 0, v135, vcc
	ds_read_b128 v[106:109], v166 offset:19520
	ds_read_b128 v[110:113], v166 offset:18496
	s_waitcnt lgkmcnt(0)
	v_pk_add_f32 v[96:97], v[108:109], 1.0 op_sel_hi:[1,0]
	v_pk_add_f32 v[106:107], v[106:107], 1.0 op_sel_hi:[1,0]
	s_waitcnt lgkmcnt(0)
	v_pk_fma_f32 v[88:89], v[88:89], v[96:97], v[112:113]
	v_pk_fma_f32 v[86:87], v[86:87], v[106:107], v[110:111]
	s_nop 0
	v_cvt_pk_bf16_f32 v86, v86, v87
	v_cvt_pk_bf16_f32 v87, v88, v89
	global_store_dwordx2 v[100:101], v[86:87], off offset:32
.LBB0_377:
	ds_read_b128 v[86:89], v166 offset:16896
	ds_read_b128 v[106:109], v166 offset:17920
	v_sub_f32_e32 v83, v83, v102
	v_sub_f32_e32 v82, v82, v102
	v_sub_f32_e32 v85, v85, v102
	v_sub_f32_e32 v84, v84, v102
	v_pk_mul_f32 v[84:85], v[94:95], v[84:85]
	v_pk_mul_f32 v[82:83], v[104:105], v[82:83]
	s_and_b64 vcc, exec, s[42:43]
	s_waitcnt lgkmcnt(0)
	v_pk_fma_f32 v[82:83], v[82:83], v[86:87], v[106:107]
	v_pk_fma_f32 v[84:85], v[84:85], v[88:89], v[108:109]
	v_cndmask_b32_e64 v83, v215, v83, s[40:41]
	v_cndmask_b32_e64 v85, v215, v85, s[40:41]
	v_cndmask_b32_e64 v84, v215, v84, s[40:41]
	v_cndmask_b32_e64 v82, v215, v82, s[40:41]
	global_store_dwordx4 v[98:99], v[82:85], off offset:512
	s_cbranch_vccnz .LBB0_379
	v_add_co_u32_e32 v86, vcc, 0x1000, v134
	s_nop 1
	v_addc_co_u32_e32 v87, vcc, 0, v135, vcc
	ds_read_b128 v[86:89], v166 offset:19968
	s_nop 0
	ds_read_b128 v[94:97], v166 offset:18944
	s_waitcnt lgkmcnt(0)
	v_pk_add_f32 v[88:89], v[88:89], 1.0 op_sel_hi:[1,0]
	v_pk_add_f32 v[86:87], v[86:87], 1.0 op_sel_hi:[1,0]
	s_waitcnt lgkmcnt(0)
	v_pk_fma_f32 v[84:85], v[84:85], v[88:89], v[96:97]
	v_pk_fma_f32 v[82:83], v[82:83], v[86:87], v[94:95]
	s_nop 0
	v_cvt_pk_bf16_f32 v82, v82, v83
	v_cvt_pk_bf16_f32 v83, v84, v85
	global_store_dwordx2 v[100:101], v[82:83], off offset:256
.LBB0_379:
	ds_read_b128 v[82:85], v166 offset:16960
	ds_read_b128 v[86:89], v166 offset:17984
	v_sub_f32_e32 v71, v71, v102
	v_sub_f32_e32 v70, v70, v102
	v_sub_f32_e32 v73, v73, v102
	v_sub_f32_e32 v72, v72, v102
	v_mov_b32_e32 v102, v103
	v_pk_mul_f32 v[72:73], v[102:103], v[72:73]
	v_pk_mul_f32 v[70:71], v[104:105], v[70:71]
	s_and_b64 vcc, exec, s[42:43]
	s_waitcnt lgkmcnt(0)
	v_pk_fma_f32 v[70:71], v[70:71], v[82:83], v[86:87]
	v_pk_fma_f32 v[72:73], v[72:73], v[84:85], v[88:89]
	v_cndmask_b32_e64 v71, v215, v71, s[40:41]
	v_cndmask_b32_e64 v73, v215, v73, s[40:41]
	v_cndmask_b32_e64 v72, v215, v72, s[40:41]
	v_cndmask_b32_e64 v70, v215, v70, s[40:41]
	global_store_dwordx4 v[98:99], v[70:73], off offset:576
	s_cbranch_vccnz .LBB0_381
	v_add_co_u32_e32 v82, vcc, 0x1000, v134
	s_nop 1
	v_addc_co_u32_e32 v83, vcc, 0, v135, vcc
	ds_read_b128 v[82:85], v166 offset:20032
	s_nop 0
	ds_read_b128 v[86:89], v166 offset:19008
	s_waitcnt lgkmcnt(0)
	v_pk_add_f32 v[84:85], v[84:85], 1.0 op_sel_hi:[1,0]
	v_pk_add_f32 v[82:83], v[82:83], 1.0 op_sel_hi:[1,0]
	s_waitcnt lgkmcnt(0)
	v_pk_fma_f32 v[72:73], v[72:73], v[84:85], v[88:89]
	v_pk_fma_f32 v[70:71], v[70:71], v[82:83], v[86:87]
	s_nop 0
	v_cvt_pk_bf16_f32 v70, v70, v71
	v_cvt_pk_bf16_f32 v71, v72, v73
	global_store_dwordx2 v[100:101], v[70:71], off offset:288

.LBB0_383:
	ds_read_b128 v[70:73], v166 offset:16448
	ds_read_b128 v[90:93], v166 offset:17472
	v_mov_b32_e32 v88, v87
	v_mov_b32_e32 v89, v87
	v_sub_f32_e32 v95, v79, v86
	v_sub_f32_e32 v94, v78, v86
	v_sub_f32_e32 v81, v81, v86
	v_sub_f32_e32 v80, v80, v86
	v_mov_b32_e32 v78, v87
	v_mov_b32_e32 v79, v87
	v_pk_mul_f32 v[80:81], v[78:79], v[80:81]
	v_pk_mul_f32 v[94:95], v[88:89], v[94:95]
	s_and_b64 vcc, exec, s[42:43]
	s_waitcnt lgkmcnt(0)
	v_pk_fma_f32 v[70:71], v[94:95], v[70:71], v[90:91]
	v_pk_fma_f32 v[72:73], v[80:81], v[72:73], v[92:93]
	v_cndmask_b32_e64 v71, v215, v71, s[40:41]
	v_cndmask_b32_e64 v73, v215, v73, s[40:41]
	v_cndmask_b32_e64 v72, v215, v72, s[40:41]
	v_cndmask_b32_e64 v70, v215, v70, s[40:41]
	global_store_dwordx4 v[82:83], v[70:73], off offset:64
	s_cbranch_vccnz .LBB0_385
	v_add_co_u32_e32 v80, vcc, 0x1000, v134
	s_nop 1
	v_addc_co_u32_e32 v81, vcc, 0, v135, vcc
	ds_read_b128 v[90:93], v166 offset:19520
	ds_read_b128 v[94:97], v166 offset:18496
	s_waitcnt lgkmcnt(0)
	v_pk_add_f32 v[80:81], v[92:93], 1.0 op_sel_hi:[1,0]
	v_pk_add_f32 v[90:91], v[90:91], 1.0 op_sel_hi:[1,0]
	s_waitcnt lgkmcnt(0)
	v_pk_fma_f32 v[72:73], v[72:73], v[80:81], v[96:97]
	v_pk_fma_f32 v[70:71], v[70:71], v[90:91], v[94:95]
	s_nop 0
	v_cvt_pk_bf16_f32 v70, v70, v71
	v_cvt_pk_bf16_f32 v71, v72, v73
	global_store_dwordx2 v[84:85], v[70:71], off offset:32
.LBB0_385:
	ds_read_b128 v[70:73], v166 offset:16896
	ds_read_b128 v[90:93], v166 offset:17920
	v_sub_f32_e32 v67, v67, v86
	v_sub_f32_e32 v66, v66, v86
	v_sub_f32_e32 v69, v69, v86
	v_sub_f32_e32 v68, v68, v86
	v_pk_mul_f32 v[68:69], v[78:79], v[68:69]
	v_pk_mul_f32 v[66:67], v[88:89], v[66:67]
	s_and_b64 vcc, exec, s[42:43]
	s_waitcnt lgkmcnt(0)
	v_pk_fma_f32 v[66:67], v[66:67], v[70:71], v[90:91]
	v_pk_fma_f32 v[68:69], v[68:69], v[72:73], v[92:93]
	v_cndmask_b32_e64 v67, v215, v67, s[40:41]
	v_cndmask_b32_e64 v69, v215, v69, s[40:41]
	v_cndmask_b32_e64 v68, v215, v68, s[40:41]
	v_cndmask_b32_e64 v66, v215, v66, s[40:41]
	global_store_dwordx4 v[82:83], v[66:69], off offset:512
	s_cbranch_vccnz .LBB0_387
	v_add_co_u32_e32 v70, vcc, 0x1000, v134
	s_nop 1
	v_addc_co_u32_e32 v71, vcc, 0, v135, vcc
	ds_read_b128 v[70:73], v166 offset:19968
	s_nop 0
	ds_read_b128 v[78:81], v166 offset:18944
	s_waitcnt lgkmcnt(0)
	v_pk_add_f32 v[72:73], v[72:73], 1.0 op_sel_hi:[1,0]
	v_pk_add_f32 v[70:71], v[70:71], 1.0 op_sel_hi:[1,0]
	s_waitcnt lgkmcnt(0)
	v_pk_fma_f32 v[68:69], v[68:69], v[72:73], v[80:81]
	v_pk_fma_f32 v[66:67], v[66:67], v[70:71], v[78:79]
	s_nop 0
	v_cvt_pk_bf16_f32 v66, v66, v67
	v_cvt_pk_bf16_f32 v67, v68, v69
	global_store_dwordx2 v[84:85], v[66:67], off offset:256
.LBB0_387:
	ds_read_b128 v[66:69], v166 offset:16960
	ds_read_b128 v[70:73], v166 offset:17984
	v_sub_f32_e32 v55, v55, v86
	v_sub_f32_e32 v54, v54, v86
	v_sub_f32_e32 v57, v57, v86
	v_sub_f32_e32 v56, v56, v86
	v_mov_b32_e32 v86, v87
	v_pk_mul_f32 v[56:57], v[86:87], v[56:57]
	v_pk_mul_f32 v[54:55], v[88:89], v[54:55]
	s_and_b64 vcc, exec, s[42:43]
	s_waitcnt lgkmcnt(0)
	v_pk_fma_f32 v[54:55], v[54:55], v[66:67], v[70:71]
	v_pk_fma_f32 v[56:57], v[56:57], v[68:69], v[72:73]
	v_cndmask_b32_e64 v55, v215, v55, s[40:41]
	v_cndmask_b32_e64 v57, v215, v57, s[40:41]
	v_cndmask_b32_e64 v56, v215, v56, s[40:41]
	v_cndmask_b32_e64 v54, v215, v54, s[40:41]
	global_store_dwordx4 v[82:83], v[54:57], off offset:576
	s_cbranch_vccnz .LBB0_389
	v_add_co_u32_e32 v66, vcc, 0x1000, v134
	s_nop 1
	v_addc_co_u32_e32 v67, vcc, 0, v135, vcc
	ds_read_b128 v[66:69], v166 offset:20032
	s_nop 0
	ds_read_b128 v[70:73], v166 offset:19008
	s_waitcnt lgkmcnt(0)
	v_pk_add_f32 v[68:69], v[68:69], 1.0 op_sel_hi:[1,0]
	v_pk_add_f32 v[66:67], v[66:67], 1.0 op_sel_hi:[1,0]
	s_waitcnt lgkmcnt(0)
	v_pk_fma_f32 v[56:57], v[56:57], v[68:69], v[72:73]
	v_pk_fma_f32 v[54:55], v[54:55], v[66:67], v[70:71]
	s_nop 0
	v_cvt_pk_bf16_f32 v54, v54, v55
	v_cvt_pk_bf16_f32 v55, v56, v57
	global_store_dwordx2 v[84:85], v[54:55], off offset:288

.LBB0_391:
	ds_read_b128 v[54:57], v166 offset:16448
	ds_read_b128 v[74:77], v166 offset:17472
	v_mov_b32_e32 v72, v71
	v_mov_b32_e32 v73, v71
	v_sub_f32_e32 v79, v63, v70
	v_sub_f32_e32 v78, v62, v70
	v_sub_f32_e32 v65, v65, v70
	v_sub_f32_e32 v64, v64, v70
	v_mov_b32_e32 v62, v71
	v_mov_b32_e32 v63, v71
	v_pk_mul_f32 v[64:65], v[62:63], v[64:65]
	v_pk_mul_f32 v[78:79], v[72:73], v[78:79]
	s_and_b64 vcc, exec, s[42:43]
	s_waitcnt lgkmcnt(0)
	v_pk_fma_f32 v[54:55], v[78:79], v[54:55], v[74:75]
	v_pk_fma_f32 v[56:57], v[64:65], v[56:57], v[76:77]
	v_cndmask_b32_e64 v55, v215, v55, s[40:41]
	v_cndmask_b32_e64 v57, v215, v57, s[40:41]
	v_cndmask_b32_e64 v56, v215, v56, s[40:41]
	v_cndmask_b32_e64 v54, v215, v54, s[40:41]
	global_store_dwordx4 v[66:67], v[54:57], off offset:64
	s_cbranch_vccnz .LBB0_393
	v_add_co_u32_e32 v64, vcc, 0x1000, v134
	s_nop 1
	v_addc_co_u32_e32 v65, vcc, 0, v135, vcc
	ds_read_b128 v[74:77], v166 offset:19520
	ds_read_b128 v[78:81], v166 offset:18496
	s_waitcnt lgkmcnt(0)
	v_pk_add_f32 v[64:65], v[76:77], 1.0 op_sel_hi:[1,0]
	v_pk_add_f32 v[74:75], v[74:75], 1.0 op_sel_hi:[1,0]
	s_waitcnt lgkmcnt(0)
	v_pk_fma_f32 v[56:57], v[56:57], v[64:65], v[80:81]
	v_pk_fma_f32 v[54:55], v[54:55], v[74:75], v[78:79]
	s_nop 0
	v_cvt_pk_bf16_f32 v54, v54, v55
	v_cvt_pk_bf16_f32 v55, v56, v57
	global_store_dwordx2 v[68:69], v[54:55], off offset:32
.LBB0_393:
	ds_read_b128 v[54:57], v166 offset:16896
	ds_read_b128 v[74:77], v166 offset:17920
	v_sub_f32_e32 v51, v51, v70
	v_sub_f32_e32 v50, v50, v70
	v_sub_f32_e32 v53, v53, v70
	v_sub_f32_e32 v52, v52, v70
	v_pk_mul_f32 v[52:53], v[62:63], v[52:53]
	v_pk_mul_f32 v[50:51], v[72:73], v[50:51]
	s_and_b64 vcc, exec, s[42:43]
	s_waitcnt lgkmcnt(0)
	v_pk_fma_f32 v[50:51], v[50:51], v[54:55], v[74:75]
	v_pk_fma_f32 v[52:53], v[52:53], v[56:57], v[76:77]
	v_cndmask_b32_e64 v51, v215, v51, s[40:41]
	v_cndmask_b32_e64 v53, v215, v53, s[40:41]
	v_cndmask_b32_e64 v52, v215, v52, s[40:41]
	v_cndmask_b32_e64 v50, v215, v50, s[40:41]
	global_store_dwordx4 v[66:67], v[50:53], off offset:512
	s_cbranch_vccnz .LBB0_395
	v_add_co_u32_e32 v54, vcc, 0x1000, v134
	s_nop 1
	v_addc_co_u32_e32 v55, vcc, 0, v135, vcc
	ds_read_b128 v[54:57], v166 offset:19968
	s_nop 0
	ds_read_b128 v[62:65], v166 offset:18944
	s_waitcnt lgkmcnt(0)
	v_pk_add_f32 v[56:57], v[56:57], 1.0 op_sel_hi:[1,0]
	v_pk_add_f32 v[54:55], v[54:55], 1.0 op_sel_hi:[1,0]
	s_waitcnt lgkmcnt(0)
	v_pk_fma_f32 v[52:53], v[52:53], v[56:57], v[64:65]
	v_pk_fma_f32 v[50:51], v[50:51], v[54:55], v[62:63]
	s_nop 0
	v_cvt_pk_bf16_f32 v50, v50, v51
	v_cvt_pk_bf16_f32 v51, v52, v53
	global_store_dwordx2 v[68:69], v[50:51], off offset:256
.LBB0_395:
	ds_read_b128 v[50:53], v166 offset:16960
	ds_read_b128 v[54:57], v166 offset:17984
	v_sub_f32_e32 v39, v39, v70
	v_sub_f32_e32 v38, v38, v70
	v_sub_f32_e32 v41, v41, v70
	v_sub_f32_e32 v40, v40, v70
	v_mov_b32_e32 v70, v71
	v_pk_mul_f32 v[40:41], v[70:71], v[40:41]
	v_pk_mul_f32 v[38:39], v[72:73], v[38:39]
	s_and_b64 vcc, exec, s[42:43]
	s_waitcnt lgkmcnt(0)
	v_pk_fma_f32 v[38:39], v[38:39], v[50:51], v[54:55]
	v_pk_fma_f32 v[40:41], v[40:41], v[52:53], v[56:57]
	v_cndmask_b32_e64 v39, v215, v39, s[40:41]
	v_cndmask_b32_e64 v41, v215, v41, s[40:41]
	v_cndmask_b32_e64 v40, v215, v40, s[40:41]
	v_cndmask_b32_e64 v38, v215, v38, s[40:41]
	global_store_dwordx4 v[66:67], v[38:41], off offset:576
	s_cbranch_vccnz .LBB0_397
	v_add_co_u32_e32 v50, vcc, 0x1000, v134
	s_nop 1
	v_addc_co_u32_e32 v51, vcc, 0, v135, vcc
	ds_read_b128 v[50:53], v166 offset:20032
	s_nop 0
	ds_read_b128 v[54:57], v166 offset:19008
	s_waitcnt lgkmcnt(0)
	v_pk_add_f32 v[52:53], v[52:53], 1.0 op_sel_hi:[1,0]
	v_pk_add_f32 v[50:51], v[50:51], 1.0 op_sel_hi:[1,0]
	s_waitcnt lgkmcnt(0)
	v_pk_fma_f32 v[40:41], v[40:41], v[52:53], v[56:57]
	v_pk_fma_f32 v[38:39], v[38:39], v[50:51], v[54:55]
	s_nop 0
	v_cvt_pk_bf16_f32 v38, v38, v39
	v_cvt_pk_bf16_f32 v39, v40, v41
	global_store_dwordx2 v[68:69], v[38:39], off offset:288

.LBB0_399:
	ds_read_b128 v[38:41], v166 offset:16448
	ds_read_b128 v[58:61], v166 offset:17472
	v_mov_b32_e32 v56, v55
	v_mov_b32_e32 v57, v55
	v_sub_f32_e32 v63, v47, v54
	v_sub_f32_e32 v62, v46, v54
	v_sub_f32_e32 v49, v49, v54
	v_sub_f32_e32 v48, v48, v54
	v_mov_b32_e32 v46, v55
	v_mov_b32_e32 v47, v55
	v_pk_mul_f32 v[48:49], v[46:47], v[48:49]
	v_pk_mul_f32 v[62:63], v[56:57], v[62:63]
	s_and_b64 vcc, exec, s[42:43]
	s_waitcnt lgkmcnt(0)
	v_pk_fma_f32 v[38:39], v[62:63], v[38:39], v[58:59]
	v_pk_fma_f32 v[40:41], v[48:49], v[40:41], v[60:61]
	v_cndmask_b32_e64 v39, v215, v39, s[40:41]
	v_cndmask_b32_e64 v41, v215, v41, s[40:41]
	v_cndmask_b32_e64 v40, v215, v40, s[40:41]
	v_cndmask_b32_e64 v38, v215, v38, s[40:41]
	global_store_dwordx4 v[50:51], v[38:41], off offset:64
	s_cbranch_vccnz .LBB0_401
	v_add_co_u32_e32 v48, vcc, 0x1000, v134
	s_nop 1
	v_addc_co_u32_e32 v49, vcc, 0, v135, vcc
	ds_read_b128 v[58:61], v166 offset:19520
	ds_read_b128 v[62:65], v166 offset:18496
	s_waitcnt lgkmcnt(0)
	v_pk_add_f32 v[48:49], v[60:61], 1.0 op_sel_hi:[1,0]
	v_pk_add_f32 v[58:59], v[58:59], 1.0 op_sel_hi:[1,0]
	s_waitcnt lgkmcnt(0)
	v_pk_fma_f32 v[40:41], v[40:41], v[48:49], v[64:65]
	v_pk_fma_f32 v[38:39], v[38:39], v[58:59], v[62:63]
	s_nop 0
	v_cvt_pk_bf16_f32 v38, v38, v39
	v_cvt_pk_bf16_f32 v39, v40, v41
	global_store_dwordx2 v[52:53], v[38:39], off offset:32
.LBB0_401:
	ds_read_b128 v[38:41], v166 offset:16896
	ds_read_b128 v[58:61], v166 offset:17920
	v_sub_f32_e32 v35, v35, v54
	v_sub_f32_e32 v34, v34, v54
	v_sub_f32_e32 v37, v37, v54
	v_sub_f32_e32 v36, v36, v54
	v_pk_mul_f32 v[36:37], v[46:47], v[36:37]
	v_pk_mul_f32 v[34:35], v[56:57], v[34:35]
	s_and_b64 vcc, exec, s[42:43]
	s_waitcnt lgkmcnt(0)
	v_pk_fma_f32 v[34:35], v[34:35], v[38:39], v[58:59]
	v_pk_fma_f32 v[36:37], v[36:37], v[40:41], v[60:61]
	v_cndmask_b32_e64 v35, v215, v35, s[40:41]
	v_cndmask_b32_e64 v37, v215, v37, s[40:41]
	v_cndmask_b32_e64 v36, v215, v36, s[40:41]
	v_cndmask_b32_e64 v34, v215, v34, s[40:41]
	global_store_dwordx4 v[50:51], v[34:37], off offset:512
	s_cbranch_vccnz .LBB0_403
	v_add_co_u32_e32 v38, vcc, 0x1000, v134
	s_nop 1
	v_addc_co_u32_e32 v39, vcc, 0, v135, vcc
	ds_read_b128 v[38:41], v166 offset:19968
	s_nop 0
	ds_read_b128 v[46:49], v166 offset:18944
	s_waitcnt lgkmcnt(0)
	v_pk_add_f32 v[40:41], v[40:41], 1.0 op_sel_hi:[1,0]
	v_pk_add_f32 v[38:39], v[38:39], 1.0 op_sel_hi:[1,0]
	s_waitcnt lgkmcnt(0)
	v_pk_fma_f32 v[36:37], v[36:37], v[40:41], v[48:49]
	v_pk_fma_f32 v[34:35], v[34:35], v[38:39], v[46:47]
	s_nop 0
	v_cvt_pk_bf16_f32 v34, v34, v35
	v_cvt_pk_bf16_f32 v35, v36, v37
	global_store_dwordx2 v[52:53], v[34:35], off offset:256
.LBB0_403:
	ds_read_b128 v[34:37], v166 offset:16960
	ds_read_b128 v[38:41], v166 offset:17984
	v_sub_f32_e32 v27, v27, v54
	v_sub_f32_e32 v26, v26, v54
	v_sub_f32_e32 v29, v29, v54
	v_sub_f32_e32 v28, v28, v54
	v_mov_b32_e32 v54, v55
	v_pk_mul_f32 v[28:29], v[54:55], v[28:29]
	v_pk_mul_f32 v[26:27], v[56:57], v[26:27]
	s_and_b64 vcc, exec, s[42:43]
	s_waitcnt lgkmcnt(0)
	v_pk_fma_f32 v[26:27], v[26:27], v[34:35], v[38:39]
	v_pk_fma_f32 v[28:29], v[28:29], v[36:37], v[40:41]
	v_cndmask_b32_e64 v27, v215, v27, s[40:41]
	v_cndmask_b32_e64 v29, v215, v29, s[40:41]
	v_cndmask_b32_e64 v28, v215, v28, s[40:41]
	v_cndmask_b32_e64 v26, v215, v26, s[40:41]
	global_store_dwordx4 v[50:51], v[26:29], off offset:576
	s_cbranch_vccnz .LBB0_405
	v_add_co_u32_e32 v34, vcc, 0x1000, v134
	s_nop 1
	v_addc_co_u32_e32 v35, vcc, 0, v135, vcc
	ds_read_b128 v[34:37], v166 offset:20032
	s_nop 0
	ds_read_b128 v[38:41], v166 offset:19008
	s_waitcnt lgkmcnt(0)
	v_pk_add_f32 v[36:37], v[36:37], 1.0 op_sel_hi:[1,0]
	v_pk_add_f32 v[34:35], v[34:35], 1.0 op_sel_hi:[1,0]
	s_waitcnt lgkmcnt(0)
	v_pk_fma_f32 v[28:29], v[28:29], v[36:37], v[40:41]
	v_pk_fma_f32 v[26:27], v[26:27], v[34:35], v[38:39]
	s_nop 0
	v_cvt_pk_bf16_f32 v26, v26, v27
	v_cvt_pk_bf16_f32 v27, v28, v29
	global_store_dwordx2 v[52:53], v[26:27], off offset:288

.LBB0_407:
	ds_read_b128 v[26:29], v166 offset:16448
	ds_read_b128 v[42:45], v166 offset:17472
	v_mov_b32_e32 v40, v39
	v_mov_b32_e32 v41, v39
	v_sub_f32_e32 v47, v31, v38
	v_sub_f32_e32 v46, v30, v38
	v_sub_f32_e32 v33, v33, v38
	v_sub_f32_e32 v32, v32, v38
	v_mov_b32_e32 v30, v39
	v_mov_b32_e32 v31, v39
	v_pk_mul_f32 v[32:33], v[30:31], v[32:33]
	v_pk_mul_f32 v[46:47], v[40:41], v[46:47]
	s_and_b64 vcc, exec, s[42:43]
	s_waitcnt lgkmcnt(0)
	v_pk_fma_f32 v[26:27], v[46:47], v[26:27], v[42:43]
	v_pk_fma_f32 v[28:29], v[32:33], v[28:29], v[44:45]
	v_cndmask_b32_e64 v27, v215, v27, s[40:41]
	v_cndmask_b32_e64 v29, v215, v29, s[40:41]
	v_cndmask_b32_e64 v28, v215, v28, s[40:41]
	v_cndmask_b32_e64 v26, v215, v26, s[40:41]
	global_store_dwordx4 v[34:35], v[26:29], off offset:64
	s_cbranch_vccnz .LBB0_409
	v_add_co_u32_e32 v32, vcc, 0x1000, v134
	s_nop 1
	v_addc_co_u32_e32 v33, vcc, 0, v135, vcc
	ds_read_b128 v[42:45], v166 offset:19520
	ds_read_b128 v[46:49], v166 offset:18496
	s_waitcnt lgkmcnt(0)
	v_pk_add_f32 v[32:33], v[44:45], 1.0 op_sel_hi:[1,0]
	v_pk_add_f32 v[42:43], v[42:43], 1.0 op_sel_hi:[1,0]
	s_waitcnt lgkmcnt(0)
	v_pk_fma_f32 v[28:29], v[28:29], v[32:33], v[48:49]
	v_pk_fma_f32 v[26:27], v[26:27], v[42:43], v[46:47]
	s_nop 0
	v_cvt_pk_bf16_f32 v26, v26, v27
	v_cvt_pk_bf16_f32 v27, v28, v29
	global_store_dwordx2 v[36:37], v[26:27], off offset:32
.LBB0_409:
	ds_read_b128 v[26:29], v166 offset:16896
	ds_read_b128 v[42:45], v166 offset:17920
	v_sub_f32_e32 v23, v23, v38
	v_sub_f32_e32 v22, v22, v38
	v_sub_f32_e32 v25, v25, v38
	v_sub_f32_e32 v24, v24, v38
	v_pk_mul_f32 v[24:25], v[30:31], v[24:25]
	v_pk_mul_f32 v[22:23], v[40:41], v[22:23]
	s_and_b64 vcc, exec, s[42:43]
	s_waitcnt lgkmcnt(0)
	v_pk_fma_f32 v[22:23], v[22:23], v[26:27], v[42:43]
	v_pk_fma_f32 v[24:25], v[24:25], v[28:29], v[44:45]
	v_cndmask_b32_e64 v23, v215, v23, s[40:41]
	v_cndmask_b32_e64 v25, v215, v25, s[40:41]
	v_cndmask_b32_e64 v24, v215, v24, s[40:41]
	v_cndmask_b32_e64 v22, v215, v22, s[40:41]
	global_store_dwordx4 v[34:35], v[22:25], off offset:512
	s_cbranch_vccnz .LBB0_411
	v_add_co_u32_e32 v26, vcc, 0x1000, v134
	s_nop 1
	v_addc_co_u32_e32 v27, vcc, 0, v135, vcc
	ds_read_b128 v[26:29], v166 offset:19968
	s_nop 0
	ds_read_b128 v[30:33], v166 offset:18944
	s_waitcnt lgkmcnt(0)
	v_pk_add_f32 v[28:29], v[28:29], 1.0 op_sel_hi:[1,0]
	v_pk_add_f32 v[26:27], v[26:27], 1.0 op_sel_hi:[1,0]
	s_waitcnt lgkmcnt(0)
	v_pk_fma_f32 v[24:25], v[24:25], v[28:29], v[32:33]
	v_pk_fma_f32 v[22:23], v[22:23], v[26:27], v[30:31]
	s_nop 0
	v_cvt_pk_bf16_f32 v22, v22, v23
	v_cvt_pk_bf16_f32 v23, v24, v25
	global_store_dwordx2 v[36:37], v[22:23], off offset:256
.LBB0_411:
	ds_read_b128 v[22:25], v166 offset:16960
	ds_read_b128 v[26:29], v166 offset:17984
	v_sub_f32_e32 v19, v19, v38
	v_sub_f32_e32 v18, v18, v38
	v_sub_f32_e32 v21, v21, v38
	v_sub_f32_e32 v20, v20, v38
	v_mov_b32_e32 v38, v39
	v_pk_mul_f32 v[20:21], v[38:39], v[20:21]
	v_pk_mul_f32 v[18:19], v[40:41], v[18:19]
	s_and_b64 vcc, exec, s[42:43]
	s_waitcnt lgkmcnt(0)
	v_pk_fma_f32 v[18:19], v[18:19], v[22:23], v[26:27]
	v_pk_fma_f32 v[20:21], v[20:21], v[24:25], v[28:29]
	v_cndmask_b32_e64 v19, v215, v19, s[40:41]
	v_cndmask_b32_e64 v21, v215, v21, s[40:41]
	v_cndmask_b32_e64 v20, v215, v20, s[40:41]
	v_cndmask_b32_e64 v18, v215, v18, s[40:41]
	global_store_dwordx4 v[34:35], v[18:21], off offset:576
	s_cbranch_vccnz .LBB0_413
	v_add_co_u32_e32 v22, vcc, 0x1000, v134
	s_nop 1
	v_addc_co_u32_e32 v23, vcc, 0, v135, vcc
	ds_read_b128 v[22:25], v166 offset:20032
	s_nop 0
	ds_read_b128 v[26:29], v166 offset:19008
	s_waitcnt lgkmcnt(0)
	v_pk_add_f32 v[24:25], v[24:25], 1.0 op_sel_hi:[1,0]
	v_pk_add_f32 v[22:23], v[22:23], 1.0 op_sel_hi:[1,0]
	s_waitcnt lgkmcnt(0)
	v_pk_fma_f32 v[20:21], v[20:21], v[24:25], v[28:29]
	v_pk_fma_f32 v[18:19], v[18:19], v[22:23], v[26:27]
	s_nop 0
	v_cvt_pk_bf16_f32 v18, v18, v19
	v_cvt_pk_bf16_f32 v19, v20, v21
	global_store_dwordx2 v[36:37], v[18:19], off offset:288

.LBB0_415:
	ds_read_b128 v[24:27], v166 offset:16448
	ds_read_b128 v[28:31], v166 offset:17472
	v_mov_b32_e32 v14, v23
	v_mov_b32_e32 v15, v23
	v_sub_f32_e32 v11, v11, v22
	v_sub_f32_e32 v10, v10, v22
	v_sub_f32_e32 v13, v13, v22
	v_sub_f32_e32 v12, v12, v22
	v_mov_b32_e32 v16, v23
	v_mov_b32_e32 v17, v23
	v_pk_mul_f32 v[12:13], v[16:17], v[12:13]
	v_pk_mul_f32 v[10:11], v[14:15], v[10:11]
	s_and_b64 vcc, exec, s[42:43]
	s_waitcnt lgkmcnt(0)
	v_pk_fma_f32 v[10:11], v[10:11], v[24:25], v[28:29]
	v_pk_fma_f32 v[12:13], v[12:13], v[26:27], v[30:31]
	v_cndmask_b32_e64 v11, v215, v11, s[40:41]
	v_cndmask_b32_e64 v13, v215, v13, s[40:41]
	v_cndmask_b32_e64 v12, v215, v12, s[40:41]
	v_cndmask_b32_e64 v10, v215, v10, s[40:41]
	global_store_dwordx4 v[18:19], v[10:13], off offset:64
	s_cbranch_vccnz .LBB0_417
	v_add_co_u32_e32 v24, vcc, 0x1000, v134
	s_nop 1
	v_addc_co_u32_e32 v25, vcc, 0, v135, vcc
	ds_read_b128 v[24:27], v166 offset:19520
	s_nop 0
	ds_read_b128 v[28:31], v166 offset:18496
	s_waitcnt lgkmcnt(0)
	v_pk_add_f32 v[26:27], v[26:27], 1.0 op_sel_hi:[1,0]
	v_pk_add_f32 v[24:25], v[24:25], 1.0 op_sel_hi:[1,0]
	s_waitcnt lgkmcnt(0)
	v_pk_fma_f32 v[12:13], v[12:13], v[26:27], v[30:31]
	v_pk_fma_f32 v[10:11], v[10:11], v[24:25], v[28:29]
	s_nop 0
	v_cvt_pk_bf16_f32 v10, v10, v11
	v_cvt_pk_bf16_f32 v11, v12, v13
	global_store_dwordx2 v[20:21], v[10:11], off offset:32
.LBB0_417:
	ds_read_b128 v[10:13], v166 offset:16896
	ds_read_b128 v[24:27], v166 offset:17920
	v_sub_f32_e32 v7, v7, v22
	v_sub_f32_e32 v6, v6, v22
	v_sub_f32_e32 v9, v9, v22
	v_sub_f32_e32 v8, v8, v22
	v_pk_mul_f32 v[8:9], v[16:17], v[8:9]
	v_pk_mul_f32 v[6:7], v[14:15], v[6:7]
	s_and_b64 vcc, exec, s[42:43]
	s_waitcnt lgkmcnt(0)
	v_pk_fma_f32 v[6:7], v[6:7], v[10:11], v[24:25]
	v_pk_fma_f32 v[8:9], v[8:9], v[12:13], v[26:27]
	v_cndmask_b32_e64 v7, v215, v7, s[40:41]
	v_cndmask_b32_e64 v9, v215, v9, s[40:41]
	v_cndmask_b32_e64 v8, v215, v8, s[40:41]
	v_cndmask_b32_e64 v6, v215, v6, s[40:41]
	global_store_dwordx4 v[18:19], v[6:9], off offset:512
	s_cbranch_vccnz .LBB0_419
	v_add_co_u32_e32 v10, vcc, 0x1000, v134
	s_nop 1
	v_addc_co_u32_e32 v11, vcc, 0, v135, vcc
	ds_read_b128 v[10:13], v166 offset:19968
	s_nop 0
	ds_read_b128 v[24:27], v166 offset:18944
	s_waitcnt lgkmcnt(0)
	v_pk_add_f32 v[12:13], v[12:13], 1.0 op_sel_hi:[1,0]
	v_pk_add_f32 v[10:11], v[10:11], 1.0 op_sel_hi:[1,0]
	s_waitcnt lgkmcnt(0)
	v_pk_fma_f32 v[8:9], v[8:9], v[12:13], v[26:27]
	v_pk_fma_f32 v[6:7], v[6:7], v[10:11], v[24:25]
	s_nop 0
	v_cvt_pk_bf16_f32 v6, v6, v7
	v_cvt_pk_bf16_f32 v7, v8, v9
	global_store_dwordx2 v[20:21], v[6:7], off offset:256
.LBB0_419:
	ds_read_b128 v[6:9], v166 offset:16960
	ds_read_b128 v[10:13], v166 offset:17984
	v_sub_f32_e32 v3, v3, v22
	v_sub_f32_e32 v2, v2, v22
	v_sub_f32_e32 v5, v5, v22
	v_sub_f32_e32 v4, v4, v22
	v_mov_b32_e32 v22, v23
	v_pk_mul_f32 v[4:5], v[22:23], v[4:5]
	v_pk_mul_f32 v[2:3], v[14:15], v[2:3]
	s_and_b64 vcc, exec, s[42:43]
	s_waitcnt lgkmcnt(0)
	v_pk_fma_f32 v[2:3], v[2:3], v[6:7], v[10:11]
	v_pk_fma_f32 v[4:5], v[4:5], v[8:9], v[12:13]
	v_cndmask_b32_e64 v3, v215, v3, s[40:41]
	v_cndmask_b32_e64 v5, v215, v5, s[40:41]
	v_cndmask_b32_e64 v4, v215, v4, s[40:41]
	v_cndmask_b32_e64 v2, v215, v2, s[40:41]
	global_store_dwordx4 v[18:19], v[2:5], off offset:576
	s_cbranch_vccnz .LBB0_421
	v_add_co_u32_e32 v6, vcc, 0x1000, v134
	s_nop 1
	v_addc_co_u32_e32 v7, vcc, 0, v135, vcc
	ds_read_b128 v[6:9], v166 offset:20032
	s_nop 0
	ds_read_b128 v[10:13], v166 offset:19008
	s_waitcnt lgkmcnt(0)
	v_pk_add_f32 v[8:9], v[8:9], 1.0 op_sel_hi:[1,0]
	v_pk_add_f32 v[6:7], v[6:7], 1.0 op_sel_hi:[1,0]
	s_waitcnt lgkmcnt(0)
	v_pk_fma_f32 v[4:5], v[4:5], v[8:9], v[12:13]
	v_pk_fma_f32 v[2:3], v[2:3], v[6:7], v[10:11]
	s_nop 0
	v_cvt_pk_bf16_f32 v2, v2, v3
	v_cvt_pk_bf16_f32 v3, v4, v5
	global_store_dwordx2 v[20:21], v[2:3], off offset:288
